# scan loop: SADDR global loads, neg-modifier instead of xor for -kk, first LDS burst before gloads
# speedup vs baseline: 1.0377x; 1.0036x over previous
; __device__ __forceinline__ void phase_scan(const Params& P, char* smem) {
;     ...
;       *(float4*)(bp + 256) = make_float4(-kk[0], -kk[1], -kk[2], -kk[3]);
;     ...
;     for (int j = 0; j < 16; ++j) {
;       if (j + 1 < 16) {
;         SCAN_LOADB(j + 1, (j + 1) & 1)
;       }
;       __builtin_amdgcn_sched_barrier(0);
; #pragma unroll
;       for (int u = 0; u < 2; ++u) {
;         const int sl2 = j & 1;
;         const int st = j * 2 + u;
;         const f32x4 a4 = La[sl2][u], b4 = Lb[sl2][u], w4 = Lw[sl2][u], kd = Lk[sl2][u], r4 = Lr[sl2][u];
;         const float vv = Lv[sl2][u];
;         f32x2 p = S01 * a4.xy;
;         p = S23 * a4.zw + p;
;         float sa = p.x + p.y;
;         sa += dppf(sa, 0); yprev += dppf(yprev, 0);
;         sa += dppf(sa, 1); yprev += dppf(yprev, 1);
;         sa += dppf(sa, 2); yprev += dppf(yprev, 2);
;         sa += dppf(sa, 3); yprev += dppf(yprev, 3);
;         if (st >= 1 && st <= 16) ykeep0 = (kq == st - 1) ? yprev : ykeep0;
;         if (st >= 17) ykeep1 = (kq == st - 17) ? yprev : ykeep1;
;         const f32x2 sa2 = (f32x2){sa, sa}, vv2 = (f32x2){vv, vv};
;         const f32x2 t01 = sa2 * b4.xy + vv2 * kd.xy;
;         const f32x2 t23 = sa2 * b4.zw + vv2 * kd.zw;
;         S01 = S01 * w4.xy + t01;
;         S23 = S23 * w4.zw + t23;
;         f32x2 q = S01 * r4.xy;
;         q = S23 * r4.zw + q;
;         yprev = q.x + q.y;
;       }
.LBB0_1306:
	s_waitcnt lgkmcnt(0)
	v_pk_mul_f32 v[130:131], v[30:31], v[46:47] neg_lo:[0,1] neg_hi:[0,1]
	v_pk_mul_f32 v[54:55], v[54:55], v[86:87] op_sel_hi:[1,0]
	v_pk_fma_f32 v[130:131], v[32:33], v[48:49], v[130:131] neg_lo:[0,1,0] neg_hi:[0,1,0]
	v_pk_mul_f32 v[56:57], v[56:57], v[86:87] op_sel_hi:[1,0]
	v_add_f32_e32 v130, v130, v131
	v_pk_fma_f32 v[54:55], v[30:31], v[50:51], v[54:55]
	v_pk_fma_f32 v[56:57], v[32:33], v[52:53], v[56:57]
	v_add_f32_dpp v130, v130, v130 quad_perm:[1,0,3,2] row_mask:0xf bank_mask:0xf bound_ctrl:1
	s_nop 0
	s_nop 0
	v_add_f32_dpp v130, v130, v130 quad_perm:[2,3,0,1] row_mask:0xf bank_mask:0xf bound_ctrl:1
	s_nop 0
	s_nop 0
	v_add_f32_dpp v130, v130, v130 row_half_mirror row_mask:0xf bank_mask:0xf bound_ctrl:1
	s_nop 0
	s_nop 0
	v_add_f32_dpp v130, v130, v130 row_mirror row_mask:0xf bank_mask:0xf bound_ctrl:1
	v_pk_fma_f32 v[30:31], v[58:59], v[130:131], v[54:55] op_sel_hi:[1,0,1]
	v_pk_fma_f32 v[32:33], v[60:61], v[130:131], v[56:57] op_sel_hi:[1,0,1]
	ds_read_b128 v[88:91], v34 offset:4096
	ds_read_b128 v[108:111], v34 offset:5632
	ds_read2st64_b32 v[128:129], v35 offset0:15 offset1:21
	ds_read_b128 v[96:99], v34 offset:3584
	ds_read_b128 v[92:95], v34 offset:3328
	ds_read_b128 v[100:103], v34 offset:4352
	ds_read_b128 v[104:107], v34 offset:3072
	ds_read_b128 v[116:119], v34 offset:5120
	ds_read_b128 v[112:115], v34 offset:4864
	ds_read_b128 v[120:123], v34 offset:5888
	ds_read_b128 v[124:127], v34 offset:4608
	v_pk_mul_f32 v[130:131], v[30:31], v[66:67] neg_lo:[0,1] neg_hi:[0,1]
	v_pk_mul_f32 v[74:75], v[74:75], v[86:87] op_sel:[0,1] op_sel_hi:[1,1]
	v_pk_fma_f32 v[130:131], v[32:33], v[68:69], v[130:131] neg_lo:[0,1,0] neg_hi:[0,1,0]
	v_pk_mul_f32 v[76:77], v[76:77], v[86:87] op_sel:[0,1] op_sel_hi:[1,1]
	v_add_f32_e32 v130, v130, v131
	v_pk_fma_f32 v[74:75], v[30:31], v[70:71], v[74:75]
	v_pk_fma_f32 v[76:77], v[32:33], v[72:73], v[76:77]
	v_add_f32_dpp v130, v130, v130 quad_perm:[1,0,3,2] row_mask:0xf bank_mask:0xf bound_ctrl:1
	s_nop 0
	v_pk_mul_f32 v[134:135], v[62:63], v[30:31]
	v_add_f32_dpp v130, v130, v130 quad_perm:[2,3,0,1] row_mask:0xf bank_mask:0xf bound_ctrl:1
	s_nop 0
	v_pk_fma_f32 v[134:135], v[64:65], v[32:33], v[134:135]
	v_add_f32_dpp v130, v130, v130 row_half_mirror row_mask:0xf bank_mask:0xf bound_ctrl:1
	s_nop 0
	v_add_f32_e32 v134, v134, v135
	v_add_f32_dpp v130, v130, v130 row_mirror row_mask:0xf bank_mask:0xf bound_ctrl:1
	v_pk_fma_f32 v[30:31], v[78:79], v[130:131], v[74:75] op_sel_hi:[1,0,1]
	v_pk_fma_f32 v[32:33], v[80:81], v[130:131], v[76:77] op_sel_hi:[1,0,1]
	s_waitcnt lgkmcnt(0)
	v_pk_mul_f32 v[130:131], v[30:31], v[88:89] neg_lo:[0,1] neg_hi:[0,1]
	v_pk_mul_f32 v[96:97], v[96:97], v[128:129] op_sel_hi:[1,0]
	v_pk_fma_f32 v[130:131], v[32:33], v[90:91], v[130:131] neg_lo:[0,1,0] neg_hi:[0,1,0]
	v_pk_mul_f32 v[98:99], v[98:99], v[128:129] op_sel_hi:[1,0]
	v_add_f32_e32 v130, v130, v131
	v_pk_fma_f32 v[96:97], v[30:31], v[92:93], v[96:97]
	v_pk_fma_f32 v[98:99], v[32:33], v[94:95], v[98:99]
	v_add_f32_dpp v130, v130, v130 quad_perm:[1,0,3,2] row_mask:0xf bank_mask:0xf bound_ctrl:1
	v_add_f32_dpp v134, v134, v134 quad_perm:[1,0,3,2] row_mask:0xf bank_mask:0xf bound_ctrl:1
	v_pk_mul_f32 v[132:133], v[82:83], v[30:31]
	v_add_f32_dpp v130, v130, v130 quad_perm:[2,3,0,1] row_mask:0xf bank_mask:0xf bound_ctrl:1
	v_add_f32_dpp v134, v134, v134 quad_perm:[2,3,0,1] row_mask:0xf bank_mask:0xf bound_ctrl:1
	v_pk_fma_f32 v[132:133], v[84:85], v[32:33], v[132:133]
	v_add_f32_dpp v130, v130, v130 row_half_mirror row_mask:0xf bank_mask:0xf bound_ctrl:1
	v_add_f32_dpp v134, v134, v134 row_half_mirror row_mask:0xf bank_mask:0xf bound_ctrl:1
	v_add_f32_e32 v132, v132, v133
	v_add_f32_dpp v130, v130, v130 row_mirror row_mask:0xf bank_mask:0xf bound_ctrl:1
	v_add_f32_dpp v134, v134, v134 row_mirror row_mask:0xf bank_mask:0xf bound_ctrl:1
	v_cndmask_b32_e64 v44, 0, v134, s[36:37]
	v_pk_fma_f32 v[30:31], v[100:101], v[130:131], v[96:97] op_sel_hi:[1,0,1]
	v_pk_fma_f32 v[32:33], v[102:103], v[130:131], v[98:99] op_sel_hi:[1,0,1]
	ds_read_b128 v[46:49], v34 offset:7168
	ds_read_b128 v[66:69], v34 offset:8704
	ds_read2st64_b32 v[86:87], v35 offset0:27 offset1:33
	ds_read_b128 v[54:57], v34 offset:6656
	ds_read_b128 v[50:53], v34 offset:6400
	ds_read_b128 v[58:61], v34 offset:7424
	ds_read_b128 v[62:65], v34 offset:6144
	ds_read_b128 v[74:77], v34 offset:8192
	ds_read_b128 v[70:73], v34 offset:7936
	ds_read_b128 v[78:81], v34 offset:8960
	ds_read_b128 v[82:85], v34 offset:7680
	v_pk_mul_f32 v[130:131], v[30:31], v[108:109] neg_lo:[0,1] neg_hi:[0,1]
	v_pk_mul_f32 v[116:117], v[116:117], v[128:129] op_sel:[0,1] op_sel_hi:[1,1]
	v_pk_fma_f32 v[130:131], v[32:33], v[110:111], v[130:131] neg_lo:[0,1,0] neg_hi:[0,1,0]
	v_pk_mul_f32 v[118:119], v[118:119], v[128:129] op_sel:[0,1] op_sel_hi:[1,1]
	v_add_f32_e32 v130, v130, v131
	v_pk_fma_f32 v[116:117], v[30:31], v[112:113], v[116:117]
	v_pk_fma_f32 v[118:119], v[32:33], v[114:115], v[118:119]
	v_add_f32_dpp v130, v130, v130 quad_perm:[1,0,3,2] row_mask:0xf bank_mask:0xf bound_ctrl:1
	v_add_f32_dpp v132, v132, v132 quad_perm:[1,0,3,2] row_mask:0xf bank_mask:0xf bound_ctrl:1
	v_pk_mul_f32 v[134:135], v[104:105], v[30:31]
	v_add_f32_dpp v130, v130, v130 quad_perm:[2,3,0,1] row_mask:0xf bank_mask:0xf bound_ctrl:1
	v_add_f32_dpp v132, v132, v132 quad_perm:[2,3,0,1] row_mask:0xf bank_mask:0xf bound_ctrl:1
	v_pk_fma_f32 v[134:135], v[106:107], v[32:33], v[134:135]
	v_add_f32_dpp v130, v130, v130 row_half_mirror row_mask:0xf bank_mask:0xf bound_ctrl:1
	v_add_f32_dpp v132, v132, v132 row_half_mirror row_mask:0xf bank_mask:0xf bound_ctrl:1
	v_add_f32_e32 v134, v134, v135
	v_add_f32_dpp v130, v130, v130 row_mirror row_mask:0xf bank_mask:0xf bound_ctrl:1
	v_add_f32_dpp v132, v132, v132 row_mirror row_mask:0xf bank_mask:0xf bound_ctrl:1
	v_cndmask_b32_e64 v44, v44, v132, s[4:5]
	v_pk_fma_f32 v[30:31], v[120:121], v[130:131], v[116:117] op_sel_hi:[1,0,1]
	v_pk_fma_f32 v[32:33], v[122:123], v[130:131], v[118:119] op_sel_hi:[1,0,1]
	s_waitcnt lgkmcnt(0)
; __device__ __forceinline__ void phase_scan(const Params& P, char* smem) {
;     ...
;       *(float4*)(bp + 256) = make_float4(-kk[0], -kk[1], -kk[2], -kk[3]);
;     ...
;         const f32x4 a4 = La[sl2][u], b4 = Lb[sl2][u], w4 = Lw[sl2][u], kd = Lk[sl2][u], r4 = Lr[sl2][u];
;         const float vv = Lv[sl2][u];
;         f32x2 p = S01 * a4.xy;
;         p = S23 * a4.zw + p;
;         float sa = p.x + p.y;
;         sa += dppf(sa, 0); yprev += dppf(yprev, 0);
;         sa += dppf(sa, 1); yprev += dppf(yprev, 1);
;         sa += dppf(sa, 2); yprev += dppf(yprev, 2);
;         sa += dppf(sa, 3); yprev += dppf(yprev, 3);
;         if (st >= 1 && st <= 16) ykeep0 = (kq == st - 1) ? yprev : ykeep0;
;         if (st >= 17) ykeep1 = (kq == st - 17) ? yprev : ykeep1;
;         const f32x2 sa2 = (f32x2){sa, sa}, vv2 = (f32x2){vv, vv};
;         const f32x2 t01 = sa2 * b4.xy + vv2 * kd.xy;
;         const f32x2 t23 = sa2 * b4.zw + vv2 * kd.zw;
;         S01 = S01 * w4.xy + t01;
;         S23 = S23 * w4.zw + t23;
;         f32x2 q = S01 * r4.xy;
;         q = S23 * r4.zw + q;
;         yprev = q.x + q.y;
	v_pk_mul_f32 v[130:131], v[30:31], v[46:47] neg_lo:[0,1] neg_hi:[0,1]
	v_pk_mul_f32 v[54:55], v[54:55], v[86:87] op_sel_hi:[1,0]
	v_pk_fma_f32 v[130:131], v[32:33], v[48:49], v[130:131] neg_lo:[0,1,0] neg_hi:[0,1,0]
	v_pk_mul_f32 v[56:57], v[56:57], v[86:87] op_sel_hi:[1,0]
	v_add_f32_e32 v130, v130, v131
	v_pk_fma_f32 v[54:55], v[30:31], v[50:51], v[54:55]
	v_pk_fma_f32 v[56:57], v[32:33], v[52:53], v[56:57]
	v_add_f32_dpp v130, v130, v130 quad_perm:[1,0,3,2] row_mask:0xf bank_mask:0xf bound_ctrl:1
	v_add_f32_dpp v134, v134, v134 quad_perm:[1,0,3,2] row_mask:0xf bank_mask:0xf bound_ctrl:1
	v_pk_mul_f32 v[132:133], v[124:125], v[30:31]
	v_add_f32_dpp v130, v130, v130 quad_perm:[2,3,0,1] row_mask:0xf bank_mask:0xf bound_ctrl:1
	v_add_f32_dpp v134, v134, v134 quad_perm:[2,3,0,1] row_mask:0xf bank_mask:0xf bound_ctrl:1
	v_pk_fma_f32 v[132:133], v[126:127], v[32:33], v[132:133]
	v_add_f32_dpp v130, v130, v130 row_half_mirror row_mask:0xf bank_mask:0xf bound_ctrl:1
	v_add_f32_dpp v134, v134, v134 row_half_mirror row_mask:0xf bank_mask:0xf bound_ctrl:1
	v_add_f32_e32 v132, v132, v133
	v_add_f32_dpp v130, v130, v130 row_mirror row_mask:0xf bank_mask:0xf bound_ctrl:1
	v_add_f32_dpp v134, v134, v134 row_mirror row_mask:0xf bank_mask:0xf bound_ctrl:1
	v_cndmask_b32_e64 v44, v44, v134, s[6:7]
	v_pk_fma_f32 v[30:31], v[58:59], v[130:131], v[54:55] op_sel_hi:[1,0,1]
	v_pk_fma_f32 v[32:33], v[60:61], v[130:131], v[56:57] op_sel_hi:[1,0,1]
	ds_read_b128 v[88:91], v34 offset:10240
	ds_read_b128 v[108:111], v34 offset:11776
	ds_read2st64_b32 v[128:129], v35 offset0:39 offset1:45
	ds_read_b128 v[96:99], v34 offset:9728
	ds_read_b128 v[92:95], v34 offset:9472
	ds_read_b128 v[100:103], v34 offset:10496
	ds_read_b128 v[104:107], v34 offset:9216
	ds_read_b128 v[116:119], v34 offset:11264
	ds_read_b128 v[112:115], v34 offset:11008
	ds_read_b128 v[120:123], v34 offset:12032
	ds_read_b128 v[124:127], v34 offset:10752
	v_pk_mul_f32 v[130:131], v[30:31], v[66:67] neg_lo:[0,1] neg_hi:[0,1]
	v_pk_mul_f32 v[74:75], v[74:75], v[86:87] op_sel:[0,1] op_sel_hi:[1,1]
	v_pk_fma_f32 v[130:131], v[32:33], v[68:69], v[130:131] neg_lo:[0,1,0] neg_hi:[0,1,0]
	v_pk_mul_f32 v[76:77], v[76:77], v[86:87] op_sel:[0,1] op_sel_hi:[1,1]
	v_add_f32_e32 v130, v130, v131
	v_pk_fma_f32 v[74:75], v[30:31], v[70:71], v[74:75]
	v_pk_fma_f32 v[76:77], v[32:33], v[72:73], v[76:77]
	v_add_f32_dpp v130, v130, v130 quad_perm:[1,0,3,2] row_mask:0xf bank_mask:0xf bound_ctrl:1
	v_add_f32_dpp v132, v132, v132 quad_perm:[1,0,3,2] row_mask:0xf bank_mask:0xf bound_ctrl:1
	v_pk_mul_f32 v[134:135], v[62:63], v[30:31]
	v_add_f32_dpp v130, v130, v130 quad_perm:[2,3,0,1] row_mask:0xf bank_mask:0xf bound_ctrl:1
	v_add_f32_dpp v132, v132, v132 quad_perm:[2,3,0,1] row_mask:0xf bank_mask:0xf bound_ctrl:1
	v_pk_fma_f32 v[134:135], v[64:65], v[32:33], v[134:135]
	v_add_f32_dpp v130, v130, v130 row_half_mirror row_mask:0xf bank_mask:0xf bound_ctrl:1
	v_add_f32_dpp v132, v132, v132 row_half_mirror row_mask:0xf bank_mask:0xf bound_ctrl:1
	v_add_f32_e32 v134, v134, v135
	v_add_f32_dpp v130, v130, v130 row_mirror row_mask:0xf bank_mask:0xf bound_ctrl:1
	v_add_f32_dpp v132, v132, v132 row_mirror row_mask:0xf bank_mask:0xf bound_ctrl:1
	v_cndmask_b32_e64 v44, v44, v132, s[8:9]
	v_pk_fma_f32 v[30:31], v[78:79], v[130:131], v[74:75] op_sel_hi:[1,0,1]
	v_pk_fma_f32 v[32:33], v[80:81], v[130:131], v[76:77] op_sel_hi:[1,0,1]
	s_waitcnt lgkmcnt(0)
	v_pk_mul_f32 v[130:131], v[30:31], v[88:89] neg_lo:[0,1] neg_hi:[0,1]
	v_pk_mul_f32 v[96:97], v[96:97], v[128:129] op_sel_hi:[1,0]
	v_pk_fma_f32 v[130:131], v[32:33], v[90:91], v[130:131] neg_lo:[0,1,0] neg_hi:[0,1,0]
	v_pk_mul_f32 v[98:99], v[98:99], v[128:129] op_sel_hi:[1,0]
	v_add_f32_e32 v130, v130, v131
	v_pk_fma_f32 v[96:97], v[30:31], v[92:93], v[96:97]
	v_pk_fma_f32 v[98:99], v[32:33], v[94:95], v[98:99]
	v_add_f32_dpp v130, v130, v130 quad_perm:[1,0,3,2] row_mask:0xf bank_mask:0xf bound_ctrl:1
	v_add_f32_dpp v134, v134, v134 quad_perm:[1,0,3,2] row_mask:0xf bank_mask:0xf bound_ctrl:1
	v_pk_mul_f32 v[132:133], v[82:83], v[30:31]
	v_add_f32_dpp v130, v130, v130 quad_perm:[2,3,0,1] row_mask:0xf bank_mask:0xf bound_ctrl:1
	v_add_f32_dpp v134, v134, v134 quad_perm:[2,3,0,1] row_mask:0xf bank_mask:0xf bound_ctrl:1
	v_pk_fma_f32 v[132:133], v[84:85], v[32:33], v[132:133]
	v_add_f32_dpp v130, v130, v130 row_half_mirror row_mask:0xf bank_mask:0xf bound_ctrl:1
	v_add_f32_dpp v134, v134, v134 row_half_mirror row_mask:0xf bank_mask:0xf bound_ctrl:1
	v_add_f32_e32 v132, v132, v133
	v_add_f32_dpp v130, v130, v130 row_mirror row_mask:0xf bank_mask:0xf bound_ctrl:1
	v_add_f32_dpp v134, v134, v134 row_mirror row_mask:0xf bank_mask:0xf bound_ctrl:1
	v_cndmask_b32_e64 v44, v44, v134, s[12:13]
	v_pk_fma_f32 v[30:31], v[100:101], v[130:131], v[96:97] op_sel_hi:[1,0,1]
	v_pk_fma_f32 v[32:33], v[102:103], v[130:131], v[98:99] op_sel_hi:[1,0,1]
	ds_read_b128 v[46:49], v34 offset:13312
	ds_read_b128 v[66:69], v34 offset:14848
	ds_read2st64_b32 v[86:87], v35 offset0:51 offset1:57
	ds_read_b128 v[54:57], v34 offset:12800
	ds_read_b128 v[50:53], v34 offset:12544
	ds_read_b128 v[58:61], v34 offset:13568
	ds_read_b128 v[62:65], v34 offset:12288
	ds_read_b128 v[74:77], v34 offset:14336
	ds_read_b128 v[70:73], v34 offset:14080
	ds_read_b128 v[78:81], v34 offset:15104
	ds_read_b128 v[82:85], v34 offset:13824
	v_pk_mul_f32 v[130:131], v[30:31], v[108:109] neg_lo:[0,1] neg_hi:[0,1]
	v_pk_mul_f32 v[116:117], v[116:117], v[128:129] op_sel:[0,1] op_sel_hi:[1,1]
	v_pk_fma_f32 v[130:131], v[32:33], v[110:111], v[130:131] neg_lo:[0,1,0] neg_hi:[0,1,0]
	v_pk_mul_f32 v[118:119], v[118:119], v[128:129] op_sel:[0,1] op_sel_hi:[1,1]
	v_add_f32_e32 v130, v130, v131
	v_pk_fma_f32 v[116:117], v[30:31], v[112:113], v[116:117]
	v_pk_fma_f32 v[118:119], v[32:33], v[114:115], v[118:119]
	v_add_f32_dpp v130, v130, v130 quad_perm:[1,0,3,2] row_mask:0xf bank_mask:0xf bound_ctrl:1
	v_add_f32_dpp v132, v132, v132 quad_perm:[1,0,3,2] row_mask:0xf bank_mask:0xf bound_ctrl:1
	v_pk_mul_f32 v[134:135], v[104:105], v[30:31]
	v_add_f32_dpp v130, v130, v130 quad_perm:[2,3,0,1] row_mask:0xf bank_mask:0xf bound_ctrl:1
	v_add_f32_dpp v132, v132, v132 quad_perm:[2,3,0,1] row_mask:0xf bank_mask:0xf bound_ctrl:1
	v_pk_fma_f32 v[134:135], v[106:107], v[32:33], v[134:135]
	v_add_f32_dpp v130, v130, v130 row_half_mirror row_mask:0xf bank_mask:0xf bound_ctrl:1
	v_add_f32_dpp v132, v132, v132 row_half_mirror row_mask:0xf bank_mask:0xf bound_ctrl:1
	v_add_f32_e32 v134, v134, v135
	v_add_f32_dpp v130, v130, v130 row_mirror row_mask:0xf bank_mask:0xf bound_ctrl:1
	v_add_f32_dpp v132, v132, v132 row_mirror row_mask:0xf bank_mask:0xf bound_ctrl:1
	v_cndmask_b32_e64 v44, v44, v132, s[14:15]
	v_pk_fma_f32 v[30:31], v[120:121], v[130:131], v[116:117] op_sel_hi:[1,0,1]
	v_pk_fma_f32 v[32:33], v[122:123], v[130:131], v[118:119] op_sel_hi:[1,0,1]
	s_waitcnt lgkmcnt(0)
; __device__ __forceinline__ void phase_scan(const Params& P, char* smem) {
;     ...
;       *(float4*)(bp + 256) = make_float4(-kk[0], -kk[1], -kk[2], -kk[3]);
;     ...
;         const f32x4 a4 = La[sl2][u], b4 = Lb[sl2][u], w4 = Lw[sl2][u], kd = Lk[sl2][u], r4 = Lr[sl2][u];
;         const float vv = Lv[sl2][u];
;         f32x2 p = S01 * a4.xy;
;         p = S23 * a4.zw + p;
;         float sa = p.x + p.y;
;         sa += dppf(sa, 0); yprev += dppf(yprev, 0);
;         sa += dppf(sa, 1); yprev += dppf(yprev, 1);
;         sa += dppf(sa, 2); yprev += dppf(yprev, 2);
;         sa += dppf(sa, 3); yprev += dppf(yprev, 3);
;         if (st >= 1 && st <= 16) ykeep0 = (kq == st - 1) ? yprev : ykeep0;
;         if (st >= 17) ykeep1 = (kq == st - 17) ? yprev : ykeep1;
;         const f32x2 sa2 = (f32x2){sa, sa}, vv2 = (f32x2){vv, vv};
;         const f32x2 t01 = sa2 * b4.xy + vv2 * kd.xy;
;         const f32x2 t23 = sa2 * b4.zw + vv2 * kd.zw;
;         S01 = S01 * w4.xy + t01;
;         S23 = S23 * w4.zw + t23;
;         f32x2 q = S01 * r4.xy;
;         q = S23 * r4.zw + q;
;         yprev = q.x + q.y;
	v_pk_mul_f32 v[130:131], v[30:31], v[46:47] neg_lo:[0,1] neg_hi:[0,1]
	v_pk_mul_f32 v[54:55], v[54:55], v[86:87] op_sel_hi:[1,0]
	v_pk_fma_f32 v[130:131], v[32:33], v[48:49], v[130:131] neg_lo:[0,1,0] neg_hi:[0,1,0]
	v_pk_mul_f32 v[56:57], v[56:57], v[86:87] op_sel_hi:[1,0]
	v_add_f32_e32 v130, v130, v131
	v_pk_fma_f32 v[54:55], v[30:31], v[50:51], v[54:55]
	v_pk_fma_f32 v[56:57], v[32:33], v[52:53], v[56:57]
	v_add_f32_dpp v130, v130, v130 quad_perm:[1,0,3,2] row_mask:0xf bank_mask:0xf bound_ctrl:1
	v_add_f32_dpp v134, v134, v134 quad_perm:[1,0,3,2] row_mask:0xf bank_mask:0xf bound_ctrl:1
	v_pk_mul_f32 v[132:133], v[124:125], v[30:31]
	v_add_f32_dpp v130, v130, v130 quad_perm:[2,3,0,1] row_mask:0xf bank_mask:0xf bound_ctrl:1
	v_add_f32_dpp v134, v134, v134 quad_perm:[2,3,0,1] row_mask:0xf bank_mask:0xf bound_ctrl:1
	v_pk_fma_f32 v[132:133], v[126:127], v[32:33], v[132:133]
	v_add_f32_dpp v130, v130, v130 row_half_mirror row_mask:0xf bank_mask:0xf bound_ctrl:1
	v_add_f32_dpp v134, v134, v134 row_half_mirror row_mask:0xf bank_mask:0xf bound_ctrl:1
	v_add_f32_e32 v132, v132, v133
	v_add_f32_dpp v130, v130, v130 row_mirror row_mask:0xf bank_mask:0xf bound_ctrl:1
	v_add_f32_dpp v134, v134, v134 row_mirror row_mask:0xf bank_mask:0xf bound_ctrl:1
	v_cndmask_b32_e64 v44, v44, v134, s[16:17]
	v_pk_fma_f32 v[30:31], v[58:59], v[130:131], v[54:55] op_sel_hi:[1,0,1]
	v_pk_fma_f32 v[32:33], v[60:61], v[130:131], v[56:57] op_sel_hi:[1,0,1]
	ds_read_b128 v[88:91], v34 offset:16384
	ds_read_b128 v[108:111], v34 offset:17920
	ds_read2st64_b32 v[128:129], v35 offset0:63 offset1:69
	ds_read_b128 v[96:99], v34 offset:15872
	ds_read_b128 v[92:95], v34 offset:15616
	ds_read_b128 v[100:103], v34 offset:16640
	ds_read_b128 v[104:107], v34 offset:15360
	ds_read_b128 v[116:119], v34 offset:17408
	ds_read_b128 v[112:115], v34 offset:17152
	ds_read_b128 v[120:123], v34 offset:18176
	ds_read_b128 v[124:127], v34 offset:16896
	v_pk_mul_f32 v[130:131], v[30:31], v[66:67] neg_lo:[0,1] neg_hi:[0,1]
	v_pk_mul_f32 v[74:75], v[74:75], v[86:87] op_sel:[0,1] op_sel_hi:[1,1]
	v_pk_fma_f32 v[130:131], v[32:33], v[68:69], v[130:131] neg_lo:[0,1,0] neg_hi:[0,1,0]
	v_pk_mul_f32 v[76:77], v[76:77], v[86:87] op_sel:[0,1] op_sel_hi:[1,1]
	v_add_f32_e32 v130, v130, v131
	v_pk_fma_f32 v[74:75], v[30:31], v[70:71], v[74:75]
	v_pk_fma_f32 v[76:77], v[32:33], v[72:73], v[76:77]
	v_add_f32_dpp v130, v130, v130 quad_perm:[1,0,3,2] row_mask:0xf bank_mask:0xf bound_ctrl:1
	v_add_f32_dpp v132, v132, v132 quad_perm:[1,0,3,2] row_mask:0xf bank_mask:0xf bound_ctrl:1
	v_pk_mul_f32 v[134:135], v[62:63], v[30:31]
	v_add_f32_dpp v130, v130, v130 quad_perm:[2,3,0,1] row_mask:0xf bank_mask:0xf bound_ctrl:1
	v_add_f32_dpp v132, v132, v132 quad_perm:[2,3,0,1] row_mask:0xf bank_mask:0xf bound_ctrl:1
	v_pk_fma_f32 v[134:135], v[64:65], v[32:33], v[134:135]
	v_add_f32_dpp v130, v130, v130 row_half_mirror row_mask:0xf bank_mask:0xf bound_ctrl:1
	v_add_f32_dpp v132, v132, v132 row_half_mirror row_mask:0xf bank_mask:0xf bound_ctrl:1
	v_add_f32_e32 v134, v134, v135
	v_add_f32_dpp v130, v130, v130 row_mirror row_mask:0xf bank_mask:0xf bound_ctrl:1
	v_add_f32_dpp v132, v132, v132 row_mirror row_mask:0xf bank_mask:0xf bound_ctrl:1
	v_cndmask_b32_e64 v44, v44, v132, s[18:19]
	v_pk_fma_f32 v[30:31], v[78:79], v[130:131], v[74:75] op_sel_hi:[1,0,1]
	v_pk_fma_f32 v[32:33], v[80:81], v[130:131], v[76:77] op_sel_hi:[1,0,1]
	s_waitcnt lgkmcnt(0)
	v_pk_mul_f32 v[130:131], v[30:31], v[88:89] neg_lo:[0,1] neg_hi:[0,1]
	v_pk_mul_f32 v[96:97], v[96:97], v[128:129] op_sel_hi:[1,0]
	v_pk_fma_f32 v[130:131], v[32:33], v[90:91], v[130:131] neg_lo:[0,1,0] neg_hi:[0,1,0]
	v_pk_mul_f32 v[98:99], v[98:99], v[128:129] op_sel_hi:[1,0]
	v_add_f32_e32 v130, v130, v131
	v_pk_fma_f32 v[96:97], v[30:31], v[92:93], v[96:97]
	v_pk_fma_f32 v[98:99], v[32:33], v[94:95], v[98:99]
	v_add_f32_dpp v130, v130, v130 quad_perm:[1,0,3,2] row_mask:0xf bank_mask:0xf bound_ctrl:1
	v_add_f32_dpp v134, v134, v134 quad_perm:[1,0,3,2] row_mask:0xf bank_mask:0xf bound_ctrl:1
	v_pk_mul_f32 v[132:133], v[82:83], v[30:31]
	v_add_f32_dpp v130, v130, v130 quad_perm:[2,3,0,1] row_mask:0xf bank_mask:0xf bound_ctrl:1
	v_add_f32_dpp v134, v134, v134 quad_perm:[2,3,0,1] row_mask:0xf bank_mask:0xf bound_ctrl:1
	v_pk_fma_f32 v[132:133], v[84:85], v[32:33], v[132:133]
	v_add_f32_dpp v130, v130, v130 row_half_mirror row_mask:0xf bank_mask:0xf bound_ctrl:1
	v_add_f32_dpp v134, v134, v134 row_half_mirror row_mask:0xf bank_mask:0xf bound_ctrl:1
	v_add_f32_e32 v132, v132, v133
	v_add_f32_dpp v130, v130, v130 row_mirror row_mask:0xf bank_mask:0xf bound_ctrl:1
	v_add_f32_dpp v134, v134, v134 row_mirror row_mask:0xf bank_mask:0xf bound_ctrl:1
	v_cndmask_b32_e64 v44, v44, v134, s[20:21]
	v_pk_fma_f32 v[30:31], v[100:101], v[130:131], v[96:97] op_sel_hi:[1,0,1]
	v_pk_fma_f32 v[32:33], v[102:103], v[130:131], v[98:99] op_sel_hi:[1,0,1]
	ds_read_b128 v[46:49], v34 offset:19456
	ds_read_b128 v[66:69], v34 offset:20992
	ds_read2st64_b32 v[86:87], v35 offset0:75 offset1:81
	ds_read_b128 v[54:57], v34 offset:18944
	ds_read_b128 v[50:53], v34 offset:18688
	ds_read_b128 v[58:61], v34 offset:19712
	ds_read_b128 v[62:65], v34 offset:18432
	ds_read_b128 v[74:77], v34 offset:20480
	ds_read_b128 v[70:73], v34 offset:20224
	ds_read_b128 v[78:81], v34 offset:21248
	ds_read_b128 v[82:85], v34 offset:19968
	v_pk_mul_f32 v[130:131], v[30:31], v[108:109] neg_lo:[0,1] neg_hi:[0,1]
	v_pk_mul_f32 v[116:117], v[116:117], v[128:129] op_sel:[0,1] op_sel_hi:[1,1]
	v_pk_fma_f32 v[130:131], v[32:33], v[110:111], v[130:131] neg_lo:[0,1,0] neg_hi:[0,1,0]
	v_pk_mul_f32 v[118:119], v[118:119], v[128:129] op_sel:[0,1] op_sel_hi:[1,1]
	v_add_f32_e32 v130, v130, v131
	v_pk_fma_f32 v[116:117], v[30:31], v[112:113], v[116:117]
	v_pk_fma_f32 v[118:119], v[32:33], v[114:115], v[118:119]
	v_add_f32_dpp v130, v130, v130 quad_perm:[1,0,3,2] row_mask:0xf bank_mask:0xf bound_ctrl:1
	v_add_f32_dpp v132, v132, v132 quad_perm:[1,0,3,2] row_mask:0xf bank_mask:0xf bound_ctrl:1
	v_pk_mul_f32 v[134:135], v[104:105], v[30:31]
	v_add_f32_dpp v130, v130, v130 quad_perm:[2,3,0,1] row_mask:0xf bank_mask:0xf bound_ctrl:1
	v_add_f32_dpp v132, v132, v132 quad_perm:[2,3,0,1] row_mask:0xf bank_mask:0xf bound_ctrl:1
	v_pk_fma_f32 v[134:135], v[106:107], v[32:33], v[134:135]
	v_add_f32_dpp v130, v130, v130 row_half_mirror row_mask:0xf bank_mask:0xf bound_ctrl:1
	v_add_f32_dpp v132, v132, v132 row_half_mirror row_mask:0xf bank_mask:0xf bound_ctrl:1
	v_add_f32_e32 v134, v134, v135
	v_add_f32_dpp v130, v130, v130 row_mirror row_mask:0xf bank_mask:0xf bound_ctrl:1
	v_add_f32_dpp v132, v132, v132 row_mirror row_mask:0xf bank_mask:0xf bound_ctrl:1
	v_cndmask_b32_e64 v44, v44, v132, s[22:23]
	v_pk_fma_f32 v[30:31], v[120:121], v[130:131], v[116:117] op_sel_hi:[1,0,1]
	v_pk_fma_f32 v[32:33], v[122:123], v[130:131], v[118:119] op_sel_hi:[1,0,1]
	s_waitcnt lgkmcnt(0)
; __device__ __forceinline__ void phase_scan(const Params& P, char* smem) {
;     ...
;       *(float4*)(bp + 256) = make_float4(-kk[0], -kk[1], -kk[2], -kk[3]);
;     ...
;         const f32x4 a4 = La[sl2][u], b4 = Lb[sl2][u], w4 = Lw[sl2][u], kd = Lk[sl2][u], r4 = Lr[sl2][u];
;         const float vv = Lv[sl2][u];
;         f32x2 p = S01 * a4.xy;
;         p = S23 * a4.zw + p;
;         float sa = p.x + p.y;
;         sa += dppf(sa, 0); yprev += dppf(yprev, 0);
;         sa += dppf(sa, 1); yprev += dppf(yprev, 1);
;         sa += dppf(sa, 2); yprev += dppf(yprev, 2);
;         sa += dppf(sa, 3); yprev += dppf(yprev, 3);
;         if (st >= 1 && st <= 16) ykeep0 = (kq == st - 1) ? yprev : ykeep0;
;         if (st >= 17) ykeep1 = (kq == st - 17) ? yprev : ykeep1;
;         const f32x2 sa2 = (f32x2){sa, sa}, vv2 = (f32x2){vv, vv};
;         const f32x2 t01 = sa2 * b4.xy + vv2 * kd.xy;
;         const f32x2 t23 = sa2 * b4.zw + vv2 * kd.zw;
;         S01 = S01 * w4.xy + t01;
;         S23 = S23 * w4.zw + t23;
;         f32x2 q = S01 * r4.xy;
;         q = S23 * r4.zw + q;
;         yprev = q.x + q.y;
	v_pk_mul_f32 v[130:131], v[30:31], v[46:47] neg_lo:[0,1] neg_hi:[0,1]
	v_pk_mul_f32 v[54:55], v[54:55], v[86:87] op_sel_hi:[1,0]
	v_pk_fma_f32 v[130:131], v[32:33], v[48:49], v[130:131] neg_lo:[0,1,0] neg_hi:[0,1,0]
	v_pk_mul_f32 v[56:57], v[56:57], v[86:87] op_sel_hi:[1,0]
	v_add_f32_e32 v130, v130, v131
	v_pk_fma_f32 v[54:55], v[30:31], v[50:51], v[54:55]
	v_pk_fma_f32 v[56:57], v[32:33], v[52:53], v[56:57]
	v_add_f32_dpp v130, v130, v130 quad_perm:[1,0,3,2] row_mask:0xf bank_mask:0xf bound_ctrl:1
	v_add_f32_dpp v134, v134, v134 quad_perm:[1,0,3,2] row_mask:0xf bank_mask:0xf bound_ctrl:1
	v_pk_mul_f32 v[132:133], v[124:125], v[30:31]
	v_add_f32_dpp v130, v130, v130 quad_perm:[2,3,0,1] row_mask:0xf bank_mask:0xf bound_ctrl:1
	v_add_f32_dpp v134, v134, v134 quad_perm:[2,3,0,1] row_mask:0xf bank_mask:0xf bound_ctrl:1
	v_pk_fma_f32 v[132:133], v[126:127], v[32:33], v[132:133]
	v_add_f32_dpp v130, v130, v130 row_half_mirror row_mask:0xf bank_mask:0xf bound_ctrl:1
	v_add_f32_dpp v134, v134, v134 row_half_mirror row_mask:0xf bank_mask:0xf bound_ctrl:1
	v_add_f32_e32 v132, v132, v133
	v_add_f32_dpp v130, v130, v130 row_mirror row_mask:0xf bank_mask:0xf bound_ctrl:1
	v_add_f32_dpp v134, v134, v134 row_mirror row_mask:0xf bank_mask:0xf bound_ctrl:1
	v_cndmask_b32_e64 v44, v44, v134, s[24:25]
	v_pk_fma_f32 v[30:31], v[58:59], v[130:131], v[54:55] op_sel_hi:[1,0,1]
	v_pk_fma_f32 v[32:33], v[60:61], v[130:131], v[56:57] op_sel_hi:[1,0,1]
	ds_read_b128 v[88:91], v34 offset:22528
	ds_read_b128 v[108:111], v34 offset:24064
	ds_read2st64_b32 v[128:129], v35 offset0:87 offset1:93
	ds_read_b128 v[96:99], v34 offset:22016
	ds_read_b128 v[92:95], v34 offset:21760
	ds_read_b128 v[100:103], v34 offset:22784
	ds_read_b128 v[104:107], v34 offset:21504
	ds_read_b128 v[116:119], v34 offset:23552
	ds_read_b128 v[112:115], v34 offset:23296
	ds_read_b128 v[120:123], v34 offset:24320
	ds_read_b128 v[124:127], v34 offset:23040
	v_pk_mul_f32 v[130:131], v[30:31], v[66:67] neg_lo:[0,1] neg_hi:[0,1]
	v_pk_mul_f32 v[74:75], v[74:75], v[86:87] op_sel:[0,1] op_sel_hi:[1,1]
	v_pk_fma_f32 v[130:131], v[32:33], v[68:69], v[130:131] neg_lo:[0,1,0] neg_hi:[0,1,0]
	v_pk_mul_f32 v[76:77], v[76:77], v[86:87] op_sel:[0,1] op_sel_hi:[1,1]
	v_add_f32_e32 v130, v130, v131
	v_pk_fma_f32 v[74:75], v[30:31], v[70:71], v[74:75]
	v_pk_fma_f32 v[76:77], v[32:33], v[72:73], v[76:77]
	v_add_f32_dpp v130, v130, v130 quad_perm:[1,0,3,2] row_mask:0xf bank_mask:0xf bound_ctrl:1
	v_add_f32_dpp v132, v132, v132 quad_perm:[1,0,3,2] row_mask:0xf bank_mask:0xf bound_ctrl:1
	v_pk_mul_f32 v[134:135], v[62:63], v[30:31]
	v_add_f32_dpp v130, v130, v130 quad_perm:[2,3,0,1] row_mask:0xf bank_mask:0xf bound_ctrl:1
	v_add_f32_dpp v132, v132, v132 quad_perm:[2,3,0,1] row_mask:0xf bank_mask:0xf bound_ctrl:1
	v_pk_fma_f32 v[134:135], v[64:65], v[32:33], v[134:135]
	v_add_f32_dpp v130, v130, v130 row_half_mirror row_mask:0xf bank_mask:0xf bound_ctrl:1
	v_add_f32_dpp v132, v132, v132 row_half_mirror row_mask:0xf bank_mask:0xf bound_ctrl:1
	v_add_f32_e32 v134, v134, v135
	v_add_f32_dpp v130, v130, v130 row_mirror row_mask:0xf bank_mask:0xf bound_ctrl:1
	v_add_f32_dpp v132, v132, v132 row_mirror row_mask:0xf bank_mask:0xf bound_ctrl:1
	v_cndmask_b32_e64 v44, v44, v132, s[26:27]
	v_pk_fma_f32 v[30:31], v[78:79], v[130:131], v[74:75] op_sel_hi:[1,0,1]
	v_pk_fma_f32 v[32:33], v[80:81], v[130:131], v[76:77] op_sel_hi:[1,0,1]
	s_waitcnt lgkmcnt(0)
	v_pk_mul_f32 v[130:131], v[30:31], v[88:89] neg_lo:[0,1] neg_hi:[0,1]
	v_pk_mul_f32 v[96:97], v[96:97], v[128:129] op_sel_hi:[1,0]
	v_pk_fma_f32 v[130:131], v[32:33], v[90:91], v[130:131] neg_lo:[0,1,0] neg_hi:[0,1,0]
	v_pk_mul_f32 v[98:99], v[98:99], v[128:129] op_sel_hi:[1,0]
	v_add_f32_e32 v130, v130, v131
	v_pk_fma_f32 v[96:97], v[30:31], v[92:93], v[96:97]
	v_pk_fma_f32 v[98:99], v[32:33], v[94:95], v[98:99]
	v_add_f32_dpp v130, v130, v130 quad_perm:[1,0,3,2] row_mask:0xf bank_mask:0xf bound_ctrl:1
	v_add_f32_dpp v134, v134, v134 quad_perm:[1,0,3,2] row_mask:0xf bank_mask:0xf bound_ctrl:1
	v_pk_mul_f32 v[132:133], v[82:83], v[30:31]
	v_add_f32_dpp v130, v130, v130 quad_perm:[2,3,0,1] row_mask:0xf bank_mask:0xf bound_ctrl:1
	v_add_f32_dpp v134, v134, v134 quad_perm:[2,3,0,1] row_mask:0xf bank_mask:0xf bound_ctrl:1
	v_pk_fma_f32 v[132:133], v[84:85], v[32:33], v[132:133]
	v_add_f32_dpp v130, v130, v130 row_half_mirror row_mask:0xf bank_mask:0xf bound_ctrl:1
	v_add_f32_dpp v134, v134, v134 row_half_mirror row_mask:0xf bank_mask:0xf bound_ctrl:1
	v_add_f32_e32 v132, v132, v133
	v_add_f32_dpp v130, v130, v130 row_mirror row_mask:0xf bank_mask:0xf bound_ctrl:1
	v_add_f32_dpp v134, v134, v134 row_mirror row_mask:0xf bank_mask:0xf bound_ctrl:1
	v_cndmask_b32_e64 v44, v44, v134, s[28:29]
	v_pk_fma_f32 v[30:31], v[100:101], v[130:131], v[96:97] op_sel_hi:[1,0,1]
	v_pk_fma_f32 v[32:33], v[102:103], v[130:131], v[98:99] op_sel_hi:[1,0,1]
	ds_read_b128 v[46:49], v34 offset:25600
	ds_read_b128 v[66:69], v34 offset:27136
	ds_read2st64_b32 v[86:87], v35 offset0:99 offset1:105
	ds_read_b128 v[54:57], v34 offset:25088
	ds_read_b128 v[50:53], v34 offset:24832
	ds_read_b128 v[58:61], v34 offset:25856
	ds_read_b128 v[62:65], v34 offset:24576
	ds_read_b128 v[74:77], v34 offset:26624
	ds_read_b128 v[70:73], v34 offset:26368
	ds_read_b128 v[78:81], v34 offset:27392
	ds_read_b128 v[82:85], v34 offset:26112
	v_pk_mul_f32 v[130:131], v[30:31], v[108:109] neg_lo:[0,1] neg_hi:[0,1]
	v_pk_mul_f32 v[116:117], v[116:117], v[128:129] op_sel:[0,1] op_sel_hi:[1,1]
	v_pk_fma_f32 v[130:131], v[32:33], v[110:111], v[130:131] neg_lo:[0,1,0] neg_hi:[0,1,0]
	v_pk_mul_f32 v[118:119], v[118:119], v[128:129] op_sel:[0,1] op_sel_hi:[1,1]
	v_add_f32_e32 v130, v130, v131
	v_pk_fma_f32 v[116:117], v[30:31], v[112:113], v[116:117]
	v_pk_fma_f32 v[118:119], v[32:33], v[114:115], v[118:119]
	v_add_f32_dpp v130, v130, v130 quad_perm:[1,0,3,2] row_mask:0xf bank_mask:0xf bound_ctrl:1
	v_add_f32_dpp v132, v132, v132 quad_perm:[1,0,3,2] row_mask:0xf bank_mask:0xf bound_ctrl:1
	v_pk_mul_f32 v[134:135], v[104:105], v[30:31]
	v_add_f32_dpp v130, v130, v130 quad_perm:[2,3,0,1] row_mask:0xf bank_mask:0xf bound_ctrl:1
	v_add_f32_dpp v132, v132, v132 quad_perm:[2,3,0,1] row_mask:0xf bank_mask:0xf bound_ctrl:1
	v_pk_fma_f32 v[134:135], v[106:107], v[32:33], v[134:135]
	v_add_f32_dpp v130, v130, v130 row_half_mirror row_mask:0xf bank_mask:0xf bound_ctrl:1
	v_add_f32_dpp v132, v132, v132 row_half_mirror row_mask:0xf bank_mask:0xf bound_ctrl:1
	v_add_f32_e32 v134, v134, v135
	v_add_f32_dpp v130, v130, v130 row_mirror row_mask:0xf bank_mask:0xf bound_ctrl:1
	v_add_f32_dpp v132, v132, v132 row_mirror row_mask:0xf bank_mask:0xf bound_ctrl:1
	v_cndmask_b32_e64 v44, v44, v132, s[30:31]
	v_pk_fma_f32 v[30:31], v[120:121], v[130:131], v[116:117] op_sel_hi:[1,0,1]
	v_pk_fma_f32 v[32:33], v[122:123], v[130:131], v[118:119] op_sel_hi:[1,0,1]
	s_waitcnt lgkmcnt(0)
; __device__ __forceinline__ void phase_scan(const Params& P, char* smem) {
;     ...
;       *(float4*)(bp + 256) = make_float4(-kk[0], -kk[1], -kk[2], -kk[3]);
;     ...
;         const f32x4 a4 = La[sl2][u], b4 = Lb[sl2][u], w4 = Lw[sl2][u], kd = Lk[sl2][u], r4 = Lr[sl2][u];
;         const float vv = Lv[sl2][u];
;         f32x2 p = S01 * a4.xy;
;         p = S23 * a4.zw + p;
;         float sa = p.x + p.y;
;         sa += dppf(sa, 0); yprev += dppf(yprev, 0);
;         sa += dppf(sa, 1); yprev += dppf(yprev, 1);
;         sa += dppf(sa, 2); yprev += dppf(yprev, 2);
;         sa += dppf(sa, 3); yprev += dppf(yprev, 3);
;         if (st >= 1 && st <= 16) ykeep0 = (kq == st - 1) ? yprev : ykeep0;
;         if (st >= 17) ykeep1 = (kq == st - 17) ? yprev : ykeep1;
;         const f32x2 sa2 = (f32x2){sa, sa}, vv2 = (f32x2){vv, vv};
;         const f32x2 t01 = sa2 * b4.xy + vv2 * kd.xy;
;         const f32x2 t23 = sa2 * b4.zw + vv2 * kd.zw;
;         S01 = S01 * w4.xy + t01;
;         S23 = S23 * w4.zw + t23;
;         f32x2 q = S01 * r4.xy;
;         q = S23 * r4.zw + q;
;         yprev = q.x + q.y;
	v_pk_mul_f32 v[130:131], v[30:31], v[46:47] neg_lo:[0,1] neg_hi:[0,1]
	v_pk_mul_f32 v[54:55], v[54:55], v[86:87] op_sel_hi:[1,0]
	v_pk_fma_f32 v[130:131], v[32:33], v[48:49], v[130:131] neg_lo:[0,1,0] neg_hi:[0,1,0]
	v_pk_mul_f32 v[56:57], v[56:57], v[86:87] op_sel_hi:[1,0]
	v_add_f32_e32 v130, v130, v131
	v_pk_fma_f32 v[54:55], v[30:31], v[50:51], v[54:55]
	v_pk_fma_f32 v[56:57], v[32:33], v[52:53], v[56:57]
	v_add_f32_dpp v130, v130, v130 quad_perm:[1,0,3,2] row_mask:0xf bank_mask:0xf bound_ctrl:1
	v_add_f32_dpp v134, v134, v134 quad_perm:[1,0,3,2] row_mask:0xf bank_mask:0xf bound_ctrl:1
	v_pk_mul_f32 v[132:133], v[124:125], v[30:31]
	v_add_f32_dpp v130, v130, v130 quad_perm:[2,3,0,1] row_mask:0xf bank_mask:0xf bound_ctrl:1
	v_add_f32_dpp v134, v134, v134 quad_perm:[2,3,0,1] row_mask:0xf bank_mask:0xf bound_ctrl:1
	v_pk_fma_f32 v[132:133], v[126:127], v[32:33], v[132:133]
	v_add_f32_dpp v130, v130, v130 row_half_mirror row_mask:0xf bank_mask:0xf bound_ctrl:1
	v_add_f32_dpp v134, v134, v134 row_half_mirror row_mask:0xf bank_mask:0xf bound_ctrl:1
	v_add_f32_e32 v132, v132, v133
	v_add_f32_dpp v130, v130, v130 row_mirror row_mask:0xf bank_mask:0xf bound_ctrl:1
	v_add_f32_dpp v134, v134, v134 row_mirror row_mask:0xf bank_mask:0xf bound_ctrl:1
	v_cndmask_b32_e64 v44, v44, v134, s[34:35]
	v_pk_fma_f32 v[30:31], v[58:59], v[130:131], v[54:55] op_sel_hi:[1,0,1]
	v_pk_fma_f32 v[32:33], v[60:61], v[130:131], v[56:57] op_sel_hi:[1,0,1]
	ds_read_b128 v[88:91], v34 offset:28672
	ds_read_b128 v[108:111], v34 offset:30208
	ds_read2st64_b32 v[128:129], v35 offset0:111 offset1:117
	ds_read_b128 v[96:99], v34 offset:28160
	ds_read_b128 v[92:95], v34 offset:27904
	ds_read_b128 v[100:103], v34 offset:28928
	ds_read_b128 v[104:107], v34 offset:27648
	ds_read_b128 v[116:119], v34 offset:29696
	ds_read_b128 v[112:115], v34 offset:29440
	ds_read_b128 v[120:123], v34 offset:30464
	ds_read_b128 v[124:127], v34 offset:29184
	v_pk_mul_f32 v[130:131], v[30:31], v[66:67] neg_lo:[0,1] neg_hi:[0,1]
	v_pk_mul_f32 v[74:75], v[74:75], v[86:87] op_sel:[0,1] op_sel_hi:[1,1]
	v_pk_fma_f32 v[130:131], v[32:33], v[68:69], v[130:131] neg_lo:[0,1,0] neg_hi:[0,1,0]
	v_pk_mul_f32 v[76:77], v[76:77], v[86:87] op_sel:[0,1] op_sel_hi:[1,1]
	v_add_f32_e32 v130, v130, v131
	v_pk_fma_f32 v[74:75], v[30:31], v[70:71], v[74:75]
	v_pk_fma_f32 v[76:77], v[32:33], v[72:73], v[76:77]
	v_add_f32_dpp v130, v130, v130 quad_perm:[1,0,3,2] row_mask:0xf bank_mask:0xf bound_ctrl:1
	v_add_f32_dpp v132, v132, v132 quad_perm:[1,0,3,2] row_mask:0xf bank_mask:0xf bound_ctrl:1
	v_pk_mul_f32 v[134:135], v[62:63], v[30:31]
	v_add_f32_dpp v130, v130, v130 quad_perm:[2,3,0,1] row_mask:0xf bank_mask:0xf bound_ctrl:1
	v_add_f32_dpp v132, v132, v132 quad_perm:[2,3,0,1] row_mask:0xf bank_mask:0xf bound_ctrl:1
	v_pk_fma_f32 v[134:135], v[64:65], v[32:33], v[134:135]
	v_add_f32_dpp v130, v130, v130 row_half_mirror row_mask:0xf bank_mask:0xf bound_ctrl:1
	v_add_f32_dpp v132, v132, v132 row_half_mirror row_mask:0xf bank_mask:0xf bound_ctrl:1
	v_add_f32_e32 v134, v134, v135
	v_add_f32_dpp v130, v130, v130 row_mirror row_mask:0xf bank_mask:0xf bound_ctrl:1
	v_add_f32_dpp v132, v132, v132 row_mirror row_mask:0xf bank_mask:0xf bound_ctrl:1
	v_cndmask_b32_e64 v44, v44, v132, s[0:1]
	v_pk_fma_f32 v[30:31], v[78:79], v[130:131], v[74:75] op_sel_hi:[1,0,1]
	v_pk_fma_f32 v[32:33], v[80:81], v[130:131], v[76:77] op_sel_hi:[1,0,1]
	s_waitcnt lgkmcnt(0)
	v_pk_mul_f32 v[130:131], v[30:31], v[88:89] neg_lo:[0,1] neg_hi:[0,1]
	v_pk_mul_f32 v[96:97], v[96:97], v[128:129] op_sel_hi:[1,0]
	v_pk_fma_f32 v[130:131], v[32:33], v[90:91], v[130:131] neg_lo:[0,1,0] neg_hi:[0,1,0]
	v_pk_mul_f32 v[98:99], v[98:99], v[128:129] op_sel_hi:[1,0]
	v_add_f32_e32 v130, v130, v131
	v_pk_fma_f32 v[96:97], v[30:31], v[92:93], v[96:97]
	v_pk_fma_f32 v[98:99], v[32:33], v[94:95], v[98:99]
	v_add_f32_dpp v130, v130, v130 quad_perm:[1,0,3,2] row_mask:0xf bank_mask:0xf bound_ctrl:1
	v_add_f32_dpp v134, v134, v134 quad_perm:[1,0,3,2] row_mask:0xf bank_mask:0xf bound_ctrl:1
	v_pk_mul_f32 v[132:133], v[82:83], v[30:31]
	v_add_f32_dpp v130, v130, v130 quad_perm:[2,3,0,1] row_mask:0xf bank_mask:0xf bound_ctrl:1
	v_add_f32_dpp v134, v134, v134 quad_perm:[2,3,0,1] row_mask:0xf bank_mask:0xf bound_ctrl:1
	v_pk_fma_f32 v[132:133], v[84:85], v[32:33], v[132:133]
	v_add_f32_dpp v130, v130, v130 row_half_mirror row_mask:0xf bank_mask:0xf bound_ctrl:1
	v_add_f32_dpp v134, v134, v134 row_half_mirror row_mask:0xf bank_mask:0xf bound_ctrl:1
	v_add_f32_e32 v132, v132, v133
	v_add_f32_dpp v130, v130, v130 row_mirror row_mask:0xf bank_mask:0xf bound_ctrl:1
	v_add_f32_dpp v134, v134, v134 row_mirror row_mask:0xf bank_mask:0xf bound_ctrl:1
	v_cndmask_b32_e64 v45, 0, v134, s[36:37]
	v_pk_fma_f32 v[30:31], v[100:101], v[130:131], v[96:97] op_sel_hi:[1,0,1]
	v_pk_fma_f32 v[32:33], v[102:103], v[130:131], v[98:99] op_sel_hi:[1,0,1]
	ds_read_b128 v[46:49], v34 offset:31744
	ds_read_b128 v[66:69], v34 offset:33280
	ds_read2st64_b32 v[86:87], v35 offset0:123 offset1:129
	ds_read_b128 v[54:57], v34 offset:31232
	ds_read_b128 v[50:53], v34 offset:30976
	ds_read_b128 v[58:61], v34 offset:32000
	ds_read_b128 v[62:65], v34 offset:30720
	ds_read_b128 v[74:77], v34 offset:32768
	ds_read_b128 v[70:73], v34 offset:32512
	ds_read_b128 v[78:81], v34 offset:33536
	ds_read_b128 v[82:85], v34 offset:32256
	v_pk_mul_f32 v[130:131], v[30:31], v[108:109] neg_lo:[0,1] neg_hi:[0,1]
	v_pk_mul_f32 v[116:117], v[116:117], v[128:129] op_sel:[0,1] op_sel_hi:[1,1]
	v_pk_fma_f32 v[130:131], v[32:33], v[110:111], v[130:131] neg_lo:[0,1,0] neg_hi:[0,1,0]
	v_pk_mul_f32 v[118:119], v[118:119], v[128:129] op_sel:[0,1] op_sel_hi:[1,1]
	v_add_f32_e32 v130, v130, v131
	v_pk_fma_f32 v[116:117], v[30:31], v[112:113], v[116:117]
	v_pk_fma_f32 v[118:119], v[32:33], v[114:115], v[118:119]
	v_add_f32_dpp v130, v130, v130 quad_perm:[1,0,3,2] row_mask:0xf bank_mask:0xf bound_ctrl:1
	v_add_f32_dpp v132, v132, v132 quad_perm:[1,0,3,2] row_mask:0xf bank_mask:0xf bound_ctrl:1
	v_pk_mul_f32 v[134:135], v[104:105], v[30:31]
	v_add_f32_dpp v130, v130, v130 quad_perm:[2,3,0,1] row_mask:0xf bank_mask:0xf bound_ctrl:1
	v_add_f32_dpp v132, v132, v132 quad_perm:[2,3,0,1] row_mask:0xf bank_mask:0xf bound_ctrl:1
	v_pk_fma_f32 v[134:135], v[106:107], v[32:33], v[134:135]
	v_add_f32_dpp v130, v130, v130 row_half_mirror row_mask:0xf bank_mask:0xf bound_ctrl:1
	v_add_f32_dpp v132, v132, v132 row_half_mirror row_mask:0xf bank_mask:0xf bound_ctrl:1
	v_add_f32_e32 v134, v134, v135
	v_add_f32_dpp v130, v130, v130 row_mirror row_mask:0xf bank_mask:0xf bound_ctrl:1
	v_add_f32_dpp v132, v132, v132 row_mirror row_mask:0xf bank_mask:0xf bound_ctrl:1
	v_cndmask_b32_e64 v45, v45, v132, s[4:5]
	v_pk_fma_f32 v[30:31], v[120:121], v[130:131], v[116:117] op_sel_hi:[1,0,1]
	v_pk_fma_f32 v[32:33], v[122:123], v[130:131], v[118:119] op_sel_hi:[1,0,1]
	s_waitcnt lgkmcnt(0)
; __device__ __forceinline__ void phase_scan(const Params& P, char* smem) {
;     ...
;       *(float4*)(bp + 256) = make_float4(-kk[0], -kk[1], -kk[2], -kk[3]);
;     ...
;         const f32x4 a4 = La[sl2][u], b4 = Lb[sl2][u], w4 = Lw[sl2][u], kd = Lk[sl2][u], r4 = Lr[sl2][u];
;         const float vv = Lv[sl2][u];
;         f32x2 p = S01 * a4.xy;
;         p = S23 * a4.zw + p;
;         float sa = p.x + p.y;
;         sa += dppf(sa, 0); yprev += dppf(yprev, 0);
;         sa += dppf(sa, 1); yprev += dppf(yprev, 1);
;         sa += dppf(sa, 2); yprev += dppf(yprev, 2);
;         sa += dppf(sa, 3); yprev += dppf(yprev, 3);
;         if (st >= 1 && st <= 16) ykeep0 = (kq == st - 1) ? yprev : ykeep0;
;         if (st >= 17) ykeep1 = (kq == st - 17) ? yprev : ykeep1;
;         const f32x2 sa2 = (f32x2){sa, sa}, vv2 = (f32x2){vv, vv};
;         const f32x2 t01 = sa2 * b4.xy + vv2 * kd.xy;
;         const f32x2 t23 = sa2 * b4.zw + vv2 * kd.zw;
;         S01 = S01 * w4.xy + t01;
;         S23 = S23 * w4.zw + t23;
;         f32x2 q = S01 * r4.xy;
;         q = S23 * r4.zw + q;
;         yprev = q.x + q.y;
	v_pk_mul_f32 v[130:131], v[30:31], v[46:47] neg_lo:[0,1] neg_hi:[0,1]
	v_pk_mul_f32 v[54:55], v[54:55], v[86:87] op_sel_hi:[1,0]
	v_pk_fma_f32 v[130:131], v[32:33], v[48:49], v[130:131] neg_lo:[0,1,0] neg_hi:[0,1,0]
	v_pk_mul_f32 v[56:57], v[56:57], v[86:87] op_sel_hi:[1,0]
	v_add_f32_e32 v130, v130, v131
	v_pk_fma_f32 v[54:55], v[30:31], v[50:51], v[54:55]
	v_pk_fma_f32 v[56:57], v[32:33], v[52:53], v[56:57]
	v_add_f32_dpp v130, v130, v130 quad_perm:[1,0,3,2] row_mask:0xf bank_mask:0xf bound_ctrl:1
	v_add_f32_dpp v134, v134, v134 quad_perm:[1,0,3,2] row_mask:0xf bank_mask:0xf bound_ctrl:1
	v_pk_mul_f32 v[132:133], v[124:125], v[30:31]
	v_add_f32_dpp v130, v130, v130 quad_perm:[2,3,0,1] row_mask:0xf bank_mask:0xf bound_ctrl:1
	v_add_f32_dpp v134, v134, v134 quad_perm:[2,3,0,1] row_mask:0xf bank_mask:0xf bound_ctrl:1
	v_pk_fma_f32 v[132:133], v[126:127], v[32:33], v[132:133]
	v_add_f32_dpp v130, v130, v130 row_half_mirror row_mask:0xf bank_mask:0xf bound_ctrl:1
	v_add_f32_dpp v134, v134, v134 row_half_mirror row_mask:0xf bank_mask:0xf bound_ctrl:1
	v_add_f32_e32 v132, v132, v133
	v_add_f32_dpp v130, v130, v130 row_mirror row_mask:0xf bank_mask:0xf bound_ctrl:1
	v_add_f32_dpp v134, v134, v134 row_mirror row_mask:0xf bank_mask:0xf bound_ctrl:1
	v_cndmask_b32_e64 v45, v45, v134, s[6:7]
	v_pk_fma_f32 v[30:31], v[58:59], v[130:131], v[54:55] op_sel_hi:[1,0,1]
	v_pk_fma_f32 v[32:33], v[60:61], v[130:131], v[56:57] op_sel_hi:[1,0,1]
	ds_read_b128 v[88:91], v34 offset:34816
	ds_read_b128 v[108:111], v34 offset:36352
	ds_read2st64_b32 v[128:129], v35 offset0:135 offset1:141
	ds_read_b128 v[96:99], v34 offset:34304
	ds_read_b128 v[92:95], v34 offset:34048
	ds_read_b128 v[100:103], v34 offset:35072
	ds_read_b128 v[104:107], v34 offset:33792
	ds_read_b128 v[116:119], v34 offset:35840
	ds_read_b128 v[112:115], v34 offset:35584
	ds_read_b128 v[120:123], v34 offset:36608
	ds_read_b128 v[124:127], v34 offset:35328
	v_pk_mul_f32 v[130:131], v[30:31], v[66:67] neg_lo:[0,1] neg_hi:[0,1]
	v_pk_mul_f32 v[74:75], v[74:75], v[86:87] op_sel:[0,1] op_sel_hi:[1,1]
	v_pk_fma_f32 v[130:131], v[32:33], v[68:69], v[130:131] neg_lo:[0,1,0] neg_hi:[0,1,0]
	v_pk_mul_f32 v[76:77], v[76:77], v[86:87] op_sel:[0,1] op_sel_hi:[1,1]
	v_add_f32_e32 v130, v130, v131
	v_pk_fma_f32 v[74:75], v[30:31], v[70:71], v[74:75]
	v_pk_fma_f32 v[76:77], v[32:33], v[72:73], v[76:77]
	v_add_f32_dpp v130, v130, v130 quad_perm:[1,0,3,2] row_mask:0xf bank_mask:0xf bound_ctrl:1
	v_add_f32_dpp v132, v132, v132 quad_perm:[1,0,3,2] row_mask:0xf bank_mask:0xf bound_ctrl:1
	v_pk_mul_f32 v[134:135], v[62:63], v[30:31]
	v_add_f32_dpp v130, v130, v130 quad_perm:[2,3,0,1] row_mask:0xf bank_mask:0xf bound_ctrl:1
	v_add_f32_dpp v132, v132, v132 quad_perm:[2,3,0,1] row_mask:0xf bank_mask:0xf bound_ctrl:1
	v_pk_fma_f32 v[134:135], v[64:65], v[32:33], v[134:135]
	v_add_f32_dpp v130, v130, v130 row_half_mirror row_mask:0xf bank_mask:0xf bound_ctrl:1
	v_add_f32_dpp v132, v132, v132 row_half_mirror row_mask:0xf bank_mask:0xf bound_ctrl:1
	v_add_f32_e32 v134, v134, v135
	v_add_f32_dpp v130, v130, v130 row_mirror row_mask:0xf bank_mask:0xf bound_ctrl:1
	v_add_f32_dpp v132, v132, v132 row_mirror row_mask:0xf bank_mask:0xf bound_ctrl:1
	v_cndmask_b32_e64 v45, v45, v132, s[8:9]
	v_pk_fma_f32 v[30:31], v[78:79], v[130:131], v[74:75] op_sel_hi:[1,0,1]
	v_pk_fma_f32 v[32:33], v[80:81], v[130:131], v[76:77] op_sel_hi:[1,0,1]
	s_waitcnt lgkmcnt(0)
	v_pk_mul_f32 v[130:131], v[30:31], v[88:89] neg_lo:[0,1] neg_hi:[0,1]
	v_pk_mul_f32 v[96:97], v[96:97], v[128:129] op_sel_hi:[1,0]
	v_pk_fma_f32 v[130:131], v[32:33], v[90:91], v[130:131] neg_lo:[0,1,0] neg_hi:[0,1,0]
	v_pk_mul_f32 v[98:99], v[98:99], v[128:129] op_sel_hi:[1,0]
	v_add_f32_e32 v130, v130, v131
	v_pk_fma_f32 v[96:97], v[30:31], v[92:93], v[96:97]
	v_pk_fma_f32 v[98:99], v[32:33], v[94:95], v[98:99]
	v_add_f32_dpp v130, v130, v130 quad_perm:[1,0,3,2] row_mask:0xf bank_mask:0xf bound_ctrl:1
	v_add_f32_dpp v134, v134, v134 quad_perm:[1,0,3,2] row_mask:0xf bank_mask:0xf bound_ctrl:1
	v_pk_mul_f32 v[132:133], v[82:83], v[30:31]
	v_add_f32_dpp v130, v130, v130 quad_perm:[2,3,0,1] row_mask:0xf bank_mask:0xf bound_ctrl:1
	v_add_f32_dpp v134, v134, v134 quad_perm:[2,3,0,1] row_mask:0xf bank_mask:0xf bound_ctrl:1
	v_pk_fma_f32 v[132:133], v[84:85], v[32:33], v[132:133]
	v_add_f32_dpp v130, v130, v130 row_half_mirror row_mask:0xf bank_mask:0xf bound_ctrl:1
	v_add_f32_dpp v134, v134, v134 row_half_mirror row_mask:0xf bank_mask:0xf bound_ctrl:1
	v_add_f32_e32 v132, v132, v133
	v_add_f32_dpp v130, v130, v130 row_mirror row_mask:0xf bank_mask:0xf bound_ctrl:1
	v_add_f32_dpp v134, v134, v134 row_mirror row_mask:0xf bank_mask:0xf bound_ctrl:1
	v_cndmask_b32_e64 v45, v45, v134, s[12:13]
	v_pk_fma_f32 v[30:31], v[100:101], v[130:131], v[96:97] op_sel_hi:[1,0,1]
	v_pk_fma_f32 v[32:33], v[102:103], v[130:131], v[98:99] op_sel_hi:[1,0,1]
	ds_read_b128 v[46:49], v34 offset:37888
	ds_read_b128 v[66:69], v34 offset:39424
	ds_read2st64_b32 v[86:87], v35 offset0:147 offset1:153
	ds_read_b128 v[54:57], v34 offset:37376
	ds_read_b128 v[50:53], v34 offset:37120
	ds_read_b128 v[58:61], v34 offset:38144
	ds_read_b128 v[62:65], v34 offset:36864
	ds_read_b128 v[74:77], v34 offset:38912
	ds_read_b128 v[70:73], v34 offset:38656
	ds_read_b128 v[78:81], v34 offset:39680
	ds_read_b128 v[82:85], v34 offset:38400
	v_pk_mul_f32 v[130:131], v[30:31], v[108:109] neg_lo:[0,1] neg_hi:[0,1]
	v_pk_mul_f32 v[116:117], v[116:117], v[128:129] op_sel:[0,1] op_sel_hi:[1,1]
	v_pk_fma_f32 v[130:131], v[32:33], v[110:111], v[130:131] neg_lo:[0,1,0] neg_hi:[0,1,0]
	v_pk_mul_f32 v[118:119], v[118:119], v[128:129] op_sel:[0,1] op_sel_hi:[1,1]
	v_add_f32_e32 v130, v130, v131
	v_pk_fma_f32 v[116:117], v[30:31], v[112:113], v[116:117]
	v_pk_fma_f32 v[118:119], v[32:33], v[114:115], v[118:119]
	v_add_f32_dpp v130, v130, v130 quad_perm:[1,0,3,2] row_mask:0xf bank_mask:0xf bound_ctrl:1
	v_add_f32_dpp v132, v132, v132 quad_perm:[1,0,3,2] row_mask:0xf bank_mask:0xf bound_ctrl:1
	v_pk_mul_f32 v[134:135], v[104:105], v[30:31]
	v_add_f32_dpp v130, v130, v130 quad_perm:[2,3,0,1] row_mask:0xf bank_mask:0xf bound_ctrl:1
	v_add_f32_dpp v132, v132, v132 quad_perm:[2,3,0,1] row_mask:0xf bank_mask:0xf bound_ctrl:1
	v_pk_fma_f32 v[134:135], v[106:107], v[32:33], v[134:135]
	v_add_f32_dpp v130, v130, v130 row_half_mirror row_mask:0xf bank_mask:0xf bound_ctrl:1
	v_add_f32_dpp v132, v132, v132 row_half_mirror row_mask:0xf bank_mask:0xf bound_ctrl:1
	v_add_f32_e32 v134, v134, v135
	v_add_f32_dpp v130, v130, v130 row_mirror row_mask:0xf bank_mask:0xf bound_ctrl:1
	v_add_f32_dpp v132, v132, v132 row_mirror row_mask:0xf bank_mask:0xf bound_ctrl:1
	v_cndmask_b32_e64 v45, v45, v132, s[14:15]
	v_pk_fma_f32 v[30:31], v[120:121], v[130:131], v[116:117] op_sel_hi:[1,0,1]
	v_pk_fma_f32 v[32:33], v[122:123], v[130:131], v[118:119] op_sel_hi:[1,0,1]
	s_waitcnt lgkmcnt(0)
; __device__ __forceinline__ void phase_scan(const Params& P, char* smem) {
;     ...
;       *(float4*)(bp + 256) = make_float4(-kk[0], -kk[1], -kk[2], -kk[3]);
;     ...
;         const f32x4 a4 = La[sl2][u], b4 = Lb[sl2][u], w4 = Lw[sl2][u], kd = Lk[sl2][u], r4 = Lr[sl2][u];
;         const float vv = Lv[sl2][u];
;         f32x2 p = S01 * a4.xy;
;         p = S23 * a4.zw + p;
;         float sa = p.x + p.y;
;         sa += dppf(sa, 0); yprev += dppf(yprev, 0);
;         sa += dppf(sa, 1); yprev += dppf(yprev, 1);
;         sa += dppf(sa, 2); yprev += dppf(yprev, 2);
;         sa += dppf(sa, 3); yprev += dppf(yprev, 3);
;         if (st >= 1 && st <= 16) ykeep0 = (kq == st - 1) ? yprev : ykeep0;
;         if (st >= 17) ykeep1 = (kq == st - 17) ? yprev : ykeep1;
;         const f32x2 sa2 = (f32x2){sa, sa}, vv2 = (f32x2){vv, vv};
;         const f32x2 t01 = sa2 * b4.xy + vv2 * kd.xy;
;         const f32x2 t23 = sa2 * b4.zw + vv2 * kd.zw;
;         S01 = S01 * w4.xy + t01;
;         S23 = S23 * w4.zw + t23;
;         f32x2 q = S01 * r4.xy;
;         q = S23 * r4.zw + q;
;         yprev = q.x + q.y;
	v_pk_mul_f32 v[130:131], v[30:31], v[46:47] neg_lo:[0,1] neg_hi:[0,1]
	v_pk_mul_f32 v[54:55], v[54:55], v[86:87] op_sel_hi:[1,0]
	v_pk_fma_f32 v[130:131], v[32:33], v[48:49], v[130:131] neg_lo:[0,1,0] neg_hi:[0,1,0]
	v_pk_mul_f32 v[56:57], v[56:57], v[86:87] op_sel_hi:[1,0]
	v_add_f32_e32 v130, v130, v131
	v_pk_fma_f32 v[54:55], v[30:31], v[50:51], v[54:55]
	v_pk_fma_f32 v[56:57], v[32:33], v[52:53], v[56:57]
	v_add_f32_dpp v130, v130, v130 quad_perm:[1,0,3,2] row_mask:0xf bank_mask:0xf bound_ctrl:1
	v_add_f32_dpp v134, v134, v134 quad_perm:[1,0,3,2] row_mask:0xf bank_mask:0xf bound_ctrl:1
	v_pk_mul_f32 v[132:133], v[124:125], v[30:31]
	v_add_f32_dpp v130, v130, v130 quad_perm:[2,3,0,1] row_mask:0xf bank_mask:0xf bound_ctrl:1
	v_add_f32_dpp v134, v134, v134 quad_perm:[2,3,0,1] row_mask:0xf bank_mask:0xf bound_ctrl:1
	v_pk_fma_f32 v[132:133], v[126:127], v[32:33], v[132:133]
	v_add_f32_dpp v130, v130, v130 row_half_mirror row_mask:0xf bank_mask:0xf bound_ctrl:1
	v_add_f32_dpp v134, v134, v134 row_half_mirror row_mask:0xf bank_mask:0xf bound_ctrl:1
	v_add_f32_e32 v132, v132, v133
	v_add_f32_dpp v130, v130, v130 row_mirror row_mask:0xf bank_mask:0xf bound_ctrl:1
	v_add_f32_dpp v134, v134, v134 row_mirror row_mask:0xf bank_mask:0xf bound_ctrl:1
	v_cndmask_b32_e64 v45, v45, v134, s[16:17]
	v_pk_fma_f32 v[30:31], v[58:59], v[130:131], v[54:55] op_sel_hi:[1,0,1]
	v_pk_fma_f32 v[32:33], v[60:61], v[130:131], v[56:57] op_sel_hi:[1,0,1]
	ds_read_b128 v[88:91], v34 offset:40960
	ds_read_b128 v[108:111], v34 offset:42496
	ds_read2st64_b32 v[128:129], v35 offset0:159 offset1:165
	ds_read_b128 v[96:99], v34 offset:40448
	ds_read_b128 v[92:95], v34 offset:40192
	ds_read_b128 v[100:103], v34 offset:41216
	ds_read_b128 v[104:107], v34 offset:39936
	ds_read_b128 v[116:119], v34 offset:41984
	ds_read_b128 v[112:115], v34 offset:41728
	ds_read_b128 v[120:123], v34 offset:42752
	ds_read_b128 v[124:127], v34 offset:41472
	v_pk_mul_f32 v[130:131], v[30:31], v[66:67] neg_lo:[0,1] neg_hi:[0,1]
	v_pk_mul_f32 v[74:75], v[74:75], v[86:87] op_sel:[0,1] op_sel_hi:[1,1]
	v_pk_fma_f32 v[130:131], v[32:33], v[68:69], v[130:131] neg_lo:[0,1,0] neg_hi:[0,1,0]
	v_pk_mul_f32 v[76:77], v[76:77], v[86:87] op_sel:[0,1] op_sel_hi:[1,1]
	v_add_f32_e32 v130, v130, v131
	v_pk_fma_f32 v[74:75], v[30:31], v[70:71], v[74:75]
	v_pk_fma_f32 v[76:77], v[32:33], v[72:73], v[76:77]
	v_add_f32_dpp v130, v130, v130 quad_perm:[1,0,3,2] row_mask:0xf bank_mask:0xf bound_ctrl:1
	v_add_f32_dpp v132, v132, v132 quad_perm:[1,0,3,2] row_mask:0xf bank_mask:0xf bound_ctrl:1
	v_pk_mul_f32 v[134:135], v[62:63], v[30:31]
	v_add_f32_dpp v130, v130, v130 quad_perm:[2,3,0,1] row_mask:0xf bank_mask:0xf bound_ctrl:1
	v_add_f32_dpp v132, v132, v132 quad_perm:[2,3,0,1] row_mask:0xf bank_mask:0xf bound_ctrl:1
	v_pk_fma_f32 v[134:135], v[64:65], v[32:33], v[134:135]
	v_add_f32_dpp v130, v130, v130 row_half_mirror row_mask:0xf bank_mask:0xf bound_ctrl:1
	v_add_f32_dpp v132, v132, v132 row_half_mirror row_mask:0xf bank_mask:0xf bound_ctrl:1
	v_add_f32_e32 v134, v134, v135
	v_add_f32_dpp v130, v130, v130 row_mirror row_mask:0xf bank_mask:0xf bound_ctrl:1
	v_add_f32_dpp v132, v132, v132 row_mirror row_mask:0xf bank_mask:0xf bound_ctrl:1
	v_cndmask_b32_e64 v45, v45, v132, s[18:19]
	v_pk_fma_f32 v[30:31], v[78:79], v[130:131], v[74:75] op_sel_hi:[1,0,1]
	v_pk_fma_f32 v[32:33], v[80:81], v[130:131], v[76:77] op_sel_hi:[1,0,1]
	s_waitcnt lgkmcnt(0)
	v_pk_mul_f32 v[130:131], v[30:31], v[88:89] neg_lo:[0,1] neg_hi:[0,1]
	v_pk_mul_f32 v[96:97], v[96:97], v[128:129] op_sel_hi:[1,0]
	v_pk_fma_f32 v[130:131], v[32:33], v[90:91], v[130:131] neg_lo:[0,1,0] neg_hi:[0,1,0]
	v_pk_mul_f32 v[98:99], v[98:99], v[128:129] op_sel_hi:[1,0]
	v_add_f32_e32 v130, v130, v131
	v_pk_fma_f32 v[96:97], v[30:31], v[92:93], v[96:97]
	v_pk_fma_f32 v[98:99], v[32:33], v[94:95], v[98:99]
	v_add_f32_dpp v130, v130, v130 quad_perm:[1,0,3,2] row_mask:0xf bank_mask:0xf bound_ctrl:1
	v_add_f32_dpp v134, v134, v134 quad_perm:[1,0,3,2] row_mask:0xf bank_mask:0xf bound_ctrl:1
	v_pk_mul_f32 v[132:133], v[82:83], v[30:31]
	v_add_f32_dpp v130, v130, v130 quad_perm:[2,3,0,1] row_mask:0xf bank_mask:0xf bound_ctrl:1
	v_add_f32_dpp v134, v134, v134 quad_perm:[2,3,0,1] row_mask:0xf bank_mask:0xf bound_ctrl:1
	v_pk_fma_f32 v[132:133], v[84:85], v[32:33], v[132:133]
	v_add_f32_dpp v130, v130, v130 row_half_mirror row_mask:0xf bank_mask:0xf bound_ctrl:1
	v_add_f32_dpp v134, v134, v134 row_half_mirror row_mask:0xf bank_mask:0xf bound_ctrl:1
	v_add_f32_e32 v132, v132, v133
	v_add_f32_dpp v130, v130, v130 row_mirror row_mask:0xf bank_mask:0xf bound_ctrl:1
	v_add_f32_dpp v134, v134, v134 row_mirror row_mask:0xf bank_mask:0xf bound_ctrl:1
	v_cndmask_b32_e64 v45, v45, v134, s[20:21]
	v_pk_fma_f32 v[30:31], v[100:101], v[130:131], v[96:97] op_sel_hi:[1,0,1]
	v_pk_fma_f32 v[32:33], v[102:103], v[130:131], v[98:99] op_sel_hi:[1,0,1]
	ds_read_b128 v[46:49], v34 offset:44032
	ds_read_b128 v[66:69], v34 offset:45568
	ds_read2st64_b32 v[86:87], v35 offset0:171 offset1:177
	ds_read_b128 v[54:57], v34 offset:43520
	ds_read_b128 v[50:53], v34 offset:43264
	ds_read_b128 v[58:61], v34 offset:44288
	ds_read_b128 v[62:65], v34 offset:43008
	ds_read_b128 v[74:77], v34 offset:45056
	ds_read_b128 v[70:73], v34 offset:44800
	ds_read_b128 v[78:81], v34 offset:45824
	ds_read_b128 v[82:85], v34 offset:44544
	v_pk_mul_f32 v[130:131], v[30:31], v[108:109] neg_lo:[0,1] neg_hi:[0,1]
	v_pk_mul_f32 v[116:117], v[116:117], v[128:129] op_sel:[0,1] op_sel_hi:[1,1]
	v_pk_fma_f32 v[130:131], v[32:33], v[110:111], v[130:131] neg_lo:[0,1,0] neg_hi:[0,1,0]
	v_pk_mul_f32 v[118:119], v[118:119], v[128:129] op_sel:[0,1] op_sel_hi:[1,1]
	v_add_f32_e32 v130, v130, v131
	v_pk_fma_f32 v[116:117], v[30:31], v[112:113], v[116:117]
	v_pk_fma_f32 v[118:119], v[32:33], v[114:115], v[118:119]
	v_add_f32_dpp v130, v130, v130 quad_perm:[1,0,3,2] row_mask:0xf bank_mask:0xf bound_ctrl:1
	v_add_f32_dpp v132, v132, v132 quad_perm:[1,0,3,2] row_mask:0xf bank_mask:0xf bound_ctrl:1
	v_pk_mul_f32 v[134:135], v[104:105], v[30:31]
	v_add_f32_dpp v130, v130, v130 quad_perm:[2,3,0,1] row_mask:0xf bank_mask:0xf bound_ctrl:1
	v_add_f32_dpp v132, v132, v132 quad_perm:[2,3,0,1] row_mask:0xf bank_mask:0xf bound_ctrl:1
	v_pk_fma_f32 v[134:135], v[106:107], v[32:33], v[134:135]
	v_add_f32_dpp v130, v130, v130 row_half_mirror row_mask:0xf bank_mask:0xf bound_ctrl:1
	v_add_f32_dpp v132, v132, v132 row_half_mirror row_mask:0xf bank_mask:0xf bound_ctrl:1
	v_add_f32_e32 v134, v134, v135
	v_add_f32_dpp v130, v130, v130 row_mirror row_mask:0xf bank_mask:0xf bound_ctrl:1
	v_add_f32_dpp v132, v132, v132 row_mirror row_mask:0xf bank_mask:0xf bound_ctrl:1
	v_cndmask_b32_e64 v45, v45, v132, s[22:23]
	v_pk_fma_f32 v[30:31], v[120:121], v[130:131], v[116:117] op_sel_hi:[1,0,1]
	v_pk_fma_f32 v[32:33], v[122:123], v[130:131], v[118:119] op_sel_hi:[1,0,1]
	s_waitcnt lgkmcnt(0)
; __device__ __forceinline__ void phase_scan(const Params& P, char* smem) {
;     ...
;       *(float4*)(bp + 256) = make_float4(-kk[0], -kk[1], -kk[2], -kk[3]);
;     ...
;         const f32x4 a4 = La[sl2][u], b4 = Lb[sl2][u], w4 = Lw[sl2][u], kd = Lk[sl2][u], r4 = Lr[sl2][u];
;         const float vv = Lv[sl2][u];
;         f32x2 p = S01 * a4.xy;
;         p = S23 * a4.zw + p;
;         float sa = p.x + p.y;
;         sa += dppf(sa, 0); yprev += dppf(yprev, 0);
;         sa += dppf(sa, 1); yprev += dppf(yprev, 1);
;         sa += dppf(sa, 2); yprev += dppf(yprev, 2);
;         sa += dppf(sa, 3); yprev += dppf(yprev, 3);
;         if (st >= 1 && st <= 16) ykeep0 = (kq == st - 1) ? yprev : ykeep0;
;         if (st >= 17) ykeep1 = (kq == st - 17) ? yprev : ykeep1;
;         const f32x2 sa2 = (f32x2){sa, sa}, vv2 = (f32x2){vv, vv};
;         const f32x2 t01 = sa2 * b4.xy + vv2 * kd.xy;
;         const f32x2 t23 = sa2 * b4.zw + vv2 * kd.zw;
;         S01 = S01 * w4.xy + t01;
;         S23 = S23 * w4.zw + t23;
;         f32x2 q = S01 * r4.xy;
;         q = S23 * r4.zw + q;
;         yprev = q.x + q.y;
	v_pk_mul_f32 v[130:131], v[30:31], v[46:47] neg_lo:[0,1] neg_hi:[0,1]
	v_pk_mul_f32 v[54:55], v[54:55], v[86:87] op_sel_hi:[1,0]
	v_pk_fma_f32 v[130:131], v[32:33], v[48:49], v[130:131] neg_lo:[0,1,0] neg_hi:[0,1,0]
	v_pk_mul_f32 v[56:57], v[56:57], v[86:87] op_sel_hi:[1,0]
	v_add_f32_e32 v130, v130, v131
	v_pk_fma_f32 v[54:55], v[30:31], v[50:51], v[54:55]
	v_pk_fma_f32 v[56:57], v[32:33], v[52:53], v[56:57]
	v_add_f32_dpp v130, v130, v130 quad_perm:[1,0,3,2] row_mask:0xf bank_mask:0xf bound_ctrl:1
	v_add_f32_dpp v134, v134, v134 quad_perm:[1,0,3,2] row_mask:0xf bank_mask:0xf bound_ctrl:1
	v_pk_mul_f32 v[132:133], v[124:125], v[30:31]
	v_add_f32_dpp v130, v130, v130 quad_perm:[2,3,0,1] row_mask:0xf bank_mask:0xf bound_ctrl:1
	v_add_f32_dpp v134, v134, v134 quad_perm:[2,3,0,1] row_mask:0xf bank_mask:0xf bound_ctrl:1
	v_pk_fma_f32 v[132:133], v[126:127], v[32:33], v[132:133]
	v_add_f32_dpp v130, v130, v130 row_half_mirror row_mask:0xf bank_mask:0xf bound_ctrl:1
	v_add_f32_dpp v134, v134, v134 row_half_mirror row_mask:0xf bank_mask:0xf bound_ctrl:1
	v_add_f32_e32 v132, v132, v133
	v_add_f32_dpp v130, v130, v130 row_mirror row_mask:0xf bank_mask:0xf bound_ctrl:1
	v_add_f32_dpp v134, v134, v134 row_mirror row_mask:0xf bank_mask:0xf bound_ctrl:1
	v_cndmask_b32_e64 v45, v45, v134, s[24:25]
	v_pk_fma_f32 v[30:31], v[58:59], v[130:131], v[54:55] op_sel_hi:[1,0,1]
	v_pk_fma_f32 v[32:33], v[60:61], v[130:131], v[56:57] op_sel_hi:[1,0,1]
	ds_read_b128 v[88:91], v34 offset:47104
	ds_read_b128 v[108:111], v34 offset:48640
	ds_read2st64_b32 v[128:129], v35 offset0:183 offset1:189
	ds_read_b128 v[96:99], v34 offset:46592
	ds_read_b128 v[92:95], v34 offset:46336
	ds_read_b128 v[100:103], v34 offset:47360
	ds_read_b128 v[104:107], v34 offset:46080
	ds_read_b128 v[116:119], v34 offset:48128
	ds_read_b128 v[112:115], v34 offset:47872
	ds_read_b128 v[120:123], v34 offset:48896
	ds_read_b128 v[124:127], v34 offset:47616
	v_pk_mul_f32 v[130:131], v[30:31], v[66:67] neg_lo:[0,1] neg_hi:[0,1]
	v_pk_mul_f32 v[74:75], v[74:75], v[86:87] op_sel:[0,1] op_sel_hi:[1,1]
	v_pk_fma_f32 v[130:131], v[32:33], v[68:69], v[130:131] neg_lo:[0,1,0] neg_hi:[0,1,0]
	v_pk_mul_f32 v[76:77], v[76:77], v[86:87] op_sel:[0,1] op_sel_hi:[1,1]
	v_add_f32_e32 v130, v130, v131
	v_pk_fma_f32 v[74:75], v[30:31], v[70:71], v[74:75]
	v_pk_fma_f32 v[76:77], v[32:33], v[72:73], v[76:77]
	v_add_f32_dpp v130, v130, v130 quad_perm:[1,0,3,2] row_mask:0xf bank_mask:0xf bound_ctrl:1
	v_add_f32_dpp v132, v132, v132 quad_perm:[1,0,3,2] row_mask:0xf bank_mask:0xf bound_ctrl:1
	v_pk_mul_f32 v[134:135], v[62:63], v[30:31]
	v_add_f32_dpp v130, v130, v130 quad_perm:[2,3,0,1] row_mask:0xf bank_mask:0xf bound_ctrl:1
	v_add_f32_dpp v132, v132, v132 quad_perm:[2,3,0,1] row_mask:0xf bank_mask:0xf bound_ctrl:1
	v_pk_fma_f32 v[134:135], v[64:65], v[32:33], v[134:135]
	v_add_f32_dpp v130, v130, v130 row_half_mirror row_mask:0xf bank_mask:0xf bound_ctrl:1
	v_add_f32_dpp v132, v132, v132 row_half_mirror row_mask:0xf bank_mask:0xf bound_ctrl:1
	v_add_f32_e32 v134, v134, v135
	v_add_f32_dpp v130, v130, v130 row_mirror row_mask:0xf bank_mask:0xf bound_ctrl:1
	v_add_f32_dpp v132, v132, v132 row_mirror row_mask:0xf bank_mask:0xf bound_ctrl:1
	v_cndmask_b32_e64 v45, v45, v132, s[26:27]
	v_pk_fma_f32 v[30:31], v[78:79], v[130:131], v[74:75] op_sel_hi:[1,0,1]
	v_pk_fma_f32 v[32:33], v[80:81], v[130:131], v[76:77] op_sel_hi:[1,0,1]
	s_waitcnt lgkmcnt(0)
	v_pk_mul_f32 v[130:131], v[30:31], v[88:89] neg_lo:[0,1] neg_hi:[0,1]
	v_pk_mul_f32 v[96:97], v[96:97], v[128:129] op_sel_hi:[1,0]
	v_pk_fma_f32 v[130:131], v[32:33], v[90:91], v[130:131] neg_lo:[0,1,0] neg_hi:[0,1,0]
	v_pk_mul_f32 v[98:99], v[98:99], v[128:129] op_sel_hi:[1,0]
	v_add_f32_e32 v130, v130, v131
	v_pk_fma_f32 v[96:97], v[30:31], v[92:93], v[96:97]
	v_pk_fma_f32 v[98:99], v[32:33], v[94:95], v[98:99]
	v_add_f32_dpp v130, v130, v130 quad_perm:[1,0,3,2] row_mask:0xf bank_mask:0xf bound_ctrl:1
	v_add_f32_dpp v134, v134, v134 quad_perm:[1,0,3,2] row_mask:0xf bank_mask:0xf bound_ctrl:1
	v_pk_mul_f32 v[132:133], v[82:83], v[30:31]
	v_add_f32_dpp v130, v130, v130 quad_perm:[2,3,0,1] row_mask:0xf bank_mask:0xf bound_ctrl:1
	v_add_f32_dpp v134, v134, v134 quad_perm:[2,3,0,1] row_mask:0xf bank_mask:0xf bound_ctrl:1
	v_pk_fma_f32 v[132:133], v[84:85], v[32:33], v[132:133]
	v_add_f32_dpp v130, v130, v130 row_half_mirror row_mask:0xf bank_mask:0xf bound_ctrl:1
	v_add_f32_dpp v134, v134, v134 row_half_mirror row_mask:0xf bank_mask:0xf bound_ctrl:1
	v_add_f32_e32 v132, v132, v133
	v_add_f32_dpp v130, v130, v130 row_mirror row_mask:0xf bank_mask:0xf bound_ctrl:1
	v_add_f32_dpp v134, v134, v134 row_mirror row_mask:0xf bank_mask:0xf bound_ctrl:1
	v_cndmask_b32_e64 v45, v45, v134, s[28:29]
	v_pk_fma_f32 v[30:31], v[100:101], v[130:131], v[96:97] op_sel_hi:[1,0,1]
	v_pk_fma_f32 v[32:33], v[102:103], v[130:131], v[98:99] op_sel_hi:[1,0,1]
	v_pk_mul_f32 v[130:131], v[30:31], v[108:109] neg_lo:[0,1] neg_hi:[0,1]
	v_pk_mul_f32 v[116:117], v[116:117], v[128:129] op_sel:[0,1] op_sel_hi:[1,1]
	v_pk_fma_f32 v[130:131], v[32:33], v[110:111], v[130:131] neg_lo:[0,1,0] neg_hi:[0,1,0]
	v_pk_mul_f32 v[118:119], v[118:119], v[128:129] op_sel:[0,1] op_sel_hi:[1,1]
	v_add_f32_e32 v130, v130, v131
	v_pk_fma_f32 v[116:117], v[30:31], v[112:113], v[116:117]
	v_pk_fma_f32 v[118:119], v[32:33], v[114:115], v[118:119]
	v_add_f32_dpp v130, v130, v130 quad_perm:[1,0,3,2] row_mask:0xf bank_mask:0xf bound_ctrl:1
	v_add_f32_dpp v132, v132, v132 quad_perm:[1,0,3,2] row_mask:0xf bank_mask:0xf bound_ctrl:1
	v_pk_mul_f32 v[134:135], v[104:105], v[30:31]
	v_add_f32_dpp v130, v130, v130 quad_perm:[2,3,0,1] row_mask:0xf bank_mask:0xf bound_ctrl:1
; __device__ __forceinline__ void phase_scan(const Params& P, char* smem) {
;     ...
;         sa += dppf(sa, 3); yprev += dppf(yprev, 3);
;         if (st >= 1 && st <= 16) ykeep0 = (kq == st - 1) ? yprev : ykeep0;
;         if (st >= 17) ykeep1 = (kq == st - 17) ? yprev : ykeep1;
;         const f32x2 sa2 = (f32x2){sa, sa}, vv2 = (f32x2){vv, vv};
;         const f32x2 t01 = sa2 * b4.xy + vv2 * kd.xy;
;         const f32x2 t23 = sa2 * b4.zw + vv2 * kd.zw;
;         S01 = S01 * w4.xy + t01;
;         S23 = S23 * w4.zw + t23;
;         f32x2 q = S01 * r4.xy;
;         q = S23 * r4.zw + q;
;         yprev = q.x + q.y;
;       }
;     }
;     yprev = red16(yprev);
;     ykeep1 = (kq == 15) ? yprev : ykeep1;
;     {
;       const int kidx0 = kidx_of(ci * 32 + kq), kidx1 = kidx_of(ci * 32 + 16 + kq);
;       YZ[(size_t)(b * TPB + kidx0) * 512 + h * 64 + rg * 16 + rowl] = f2bf(ykeep0);
;       YZ[(size_t)(b * TPB + kidx1) * 512 + h * 64 + rg * 16 + rowl] = f2bf(ykeep1);
;     }
	v_add_f32_dpp v132, v132, v132 quad_perm:[2,3,0,1] row_mask:0xf bank_mask:0xf bound_ctrl:1
	v_pk_fma_f32 v[134:135], v[106:107], v[32:33], v[134:135]
	v_add_f32_dpp v130, v130, v130 row_half_mirror row_mask:0xf bank_mask:0xf bound_ctrl:1
	v_add_f32_dpp v132, v132, v132 row_half_mirror row_mask:0xf bank_mask:0xf bound_ctrl:1
	v_add_f32_e32 v134, v134, v135
	v_add_f32_dpp v130, v130, v130 row_mirror row_mask:0xf bank_mask:0xf bound_ctrl:1
	v_add_f32_dpp v132, v132, v132 row_mirror row_mask:0xf bank_mask:0xf bound_ctrl:1
	v_cndmask_b32_e64 v45, v45, v132, s[30:31]
	v_pk_fma_f32 v[30:31], v[120:121], v[130:131], v[116:117] op_sel_hi:[1,0,1]
	v_pk_fma_f32 v[32:33], v[122:123], v[130:131], v[118:119] op_sel_hi:[1,0,1]
	v_pk_mul_f32 v[132:133], v[124:125], v[30:31]
	v_add_f32_dpp v134, v134, v134 quad_perm:[1,0,3,2] row_mask:0xf bank_mask:0xf bound_ctrl:1
	v_pk_fma_f32 v[132:133], v[126:127], v[32:33], v[132:133]
	s_nop 0
	v_add_f32_e32 v132, v132, v133
	v_add_f32_dpp v134, v134, v134 quad_perm:[2,3,0,1] row_mask:0xf bank_mask:0xf bound_ctrl:1
	s_nop 0
	v_add_f32_dpp v132, v132, v132 quad_perm:[1,0,3,2] row_mask:0xf bank_mask:0xf bound_ctrl:1
	v_add_f32_dpp v134, v134, v134 row_half_mirror row_mask:0xf bank_mask:0xf bound_ctrl:1
	s_nop 0
	v_add_f32_dpp v132, v132, v132 quad_perm:[2,3,0,1] row_mask:0xf bank_mask:0xf bound_ctrl:1
	v_add_f32_dpp v134, v134, v134 row_mirror row_mask:0xf bank_mask:0xf bound_ctrl:1
	s_nop 0
	v_add_f32_dpp v132, v132, v132 row_half_mirror row_mask:0xf bank_mask:0xf bound_ctrl:1
	v_cndmask_b32_e64 v45, v45, v134, s[34:35]
	s_nop 0
	v_add_f32_dpp v132, v132, v132 row_mirror row_mask:0xf bank_mask:0xf bound_ctrl:1
	v_cndmask_b32_e64 v45, v45, v132, s[0:1]
	s_cmp_gt_u32 s33, 7
	s_cselect_b32 s38, s10, 0xff
	s_add_i32 s33, s33, 1
	v_subrev_u32_e32 v37, 32, v37
	v_add_u32_e32 v47, s38, v36
	v_subrev_u32_e32 v36, 32, v36
	v_add_u32_e32 v46, s57, v181
	v_cndmask_b32_e32 v48, v47, v46, vcc
	v_add_u32_e32 v46, 16, v46
	v_add_u32_e32 v47, -16, v47
	v_cndmask_b32_e32 v47, v47, v46, vcc
	v_bfe_u32 v46, v44, 16, 1
	v_add3_u32 v49, v44, v46, s11
	v_add_u32_e32 v50, s2, v48
	v_ashrrev_i32_e32 v51, 31, v50
	v_lshlrev_b64 v[50:51], 10, v[50:51]
	v_lshl_add_u64 v[50:51], v[12:13], 0, v[50:51]
	global_store_short_d16_hi v[50:51], v49, off
	v_bfe_u32 v46, v45, 16, 1
	v_add3_u32 v52, v45, v46, s11
	v_add_u32_e32 v54, s2, v47
	v_ashrrev_i32_e32 v55, 31, v54
	v_lshlrev_b64 v[54:55], 10, v[54:55]
	s_add_i32 s57, s57, 32
	v_lshl_add_u64 v[54:55], v[12:13], 0, v[54:55]
	s_cmpk_eq_i32 s57, 0x4100
	global_store_short_d16_hi v[54:55], v52, off
	s_barrier
	s_cbranch_scc1 .LBB0_1309
; __device__ __forceinline__ void phase_scan(const Params& P, char* smem) {
;     ...
;       r[0] = __uint_as_float(g_r[hh].x << 16); r[1] = __uint_as_float(g_r[hh].x & 0xffff0000u);
;       r[2] = __uint_as_float(g_r[hh].y << 16); r[3] = __uint_as_float(g_r[hh].y & 0xffff0000u);
;       k[0] = __uint_as_float(g_k[hh].x << 16); k[1] = __uint_as_float(g_k[hh].x & 0xffff0000u);
;       k[2] = __uint_as_float(g_k[hh].y << 16); k[3] = __uint_as_float(g_k[hh].y & 0xffff0000u);
;       v[0] = __uint_as_float(g_v[hh].x << 16); v[1] = __uint_as_float(g_v[hh].x & 0xffff0000u);
;       v[2] = __uint_as_float(g_v[hh].y << 16); v[3] = __uint_as_float(g_v[hh].y & 0xffff0000u);
;       kk[0] = __uint_as_float(g_kk[hh].x << 16); kk[1] = __uint_as_float(g_kk[hh].x & 0xffff0000u);
;       kk[2] = __uint_as_float(g_kk[hh].y << 16); kk[3] = __uint_as_float(g_kk[hh].y & 0xffff0000u);
;       dp[0] = __uint_as_float(g_dp[hh].x << 16); dp[1] = __uint_as_float(g_dp[hh].x & 0xffff0000u);
;       dp[2] = __uint_as_float(g_dp[hh].y << 16); dp[3] = __uint_as_float(g_dp[hh].y & 0xffff0000u);
;       az[0] = __uint_as_float(g_az[hh].x << 16); az[1] = __uint_as_float(g_az[hh].x & 0xffff0000u);
;       az[2] = __uint_as_float(g_az[hh].y << 16); az[3] = __uint_as_float(g_az[hh].y & 0xffff0000u);
;       float* bp = buf + (hh * 16 + sl) * 384 + k4;
;       *(float4*)(bp + 0) = make_float4(r[0], r[1], r[2], r[3]);
;       *(float4*)(bp + 64) = make_float4(1.f - dp[0], 1.f - dp[1], 1.f - dp[2], 1.f - dp[3]);
;       *(float4*)(bp + 128) = make_float4(k[0] * (1.f + (az[0] - 1.f) * ka[0]), k[1] * (1.f + (az[1] - 1.f) * ka[1]),
;                                          k[2] * (1.f + (az[2] - 1.f) * ka[2]), k[3] * (1.f + (az[3] - 1.f) * ka[3]));
;       *(float4*)(bp + 192) = make_float4(v[0], v[1], v[2], v[3]);
;       *(float4*)(bp + 256) = make_float4(-kk[0], -kk[1], -kk[2], -kk[3]);
;       *(float4*)(bp + 320) = make_float4(kk[0] * az[0], kk[1] * az[1], kk[2] * az[2], kk[3] * az[3]);
;     }
;     __syncthreads();
;     if (ci + 1 < nchunks) { SCAN_GLOAD(ci + 1) }
;     float ykeep0 = 0.f, ykeep1 = 0.f;
;     f32x4 Lr[2][2], Lw[2][2], Lk[2][2], La[2][2], Lb[2][2];
;     float Lv[2][2];
;     ...
;     SCAN_LOADB(0, 0)
.LBB0_1307:
	s_waitcnt vmcnt(11)
	v_lshlrev_b32_e32 v42, 16, v4
	v_and_b32_e32 v43, 0xffff0000, v4
	v_lshlrev_b32_e32 v44, 16, v5
	v_and_b32_e32 v45, 0xffff0000, v5
	s_waitcnt vmcnt(7)
	v_lshlrev_b32_e32 v58, 16, v14
	v_and_b32_e32 v59, 0xffff0000, v14
	v_lshlrev_b32_e32 v60, 16, v15
	v_and_b32_e32 v61, 0xffff0000, v15
	s_waitcnt vmcnt(6)
	v_lshlrev_b32_e32 v62, 16, v16
	v_and_b32_e32 v63, 0xffff0000, v16
	v_lshlrev_b32_e32 v64, 16, v17
	v_and_b32_e32 v65, 0xffff0000, v17
	ds_write_b128 v38, v[42:45]
	v_pk_add_f32 v[42:43], v[58:59], 1.0 op_sel_hi:[1,0] neg_lo:[1,0] neg_hi:[1,0]
	v_pk_add_f32 v[44:45], v[60:61], 1.0 op_sel_hi:[1,0] neg_lo:[1,0] neg_hi:[1,0]
	ds_write_b128 v38, v[42:45] offset:256
	v_pk_add_f32 v[42:43], v[62:63], -1.0 op_sel_hi:[1,0]
	v_pk_add_f32 v[44:45], v[64:65], -1.0 op_sel_hi:[1,0]
	v_lshlrev_b32_e32 v50, 16, v6
	v_and_b32_e32 v51, 0xffff0000, v6
	v_lshlrev_b32_e32 v52, 16, v7
	v_and_b32_e32 v53, 0xffff0000, v7
	v_pk_fma_f32 v[42:43], v[0:1], v[42:43], 1.0 op_sel_hi:[1,1,0]
	v_pk_fma_f32 v[44:45], v[2:3], v[44:45], 1.0 op_sel_hi:[1,1,0]
	v_lshlrev_b32_e32 v54, 16, v10
	v_and_b32_e32 v55, 0xffff0000, v10
	v_lshlrev_b32_e32 v56, 16, v11
	v_and_b32_e32 v57, 0xffff0000, v11
	v_pk_mul_f32 v[42:43], v[42:43], v[50:51]
	v_pk_mul_f32 v[44:45], v[44:45], v[52:53]
	v_lshlrev_b32_e32 v46, 16, v8
	v_and_b32_e32 v47, 0xffff0000, v8
	v_lshlrev_b32_e32 v48, 16, v9
	v_and_b32_e32 v49, 0xffff0000, v9
	ds_write_b128 v38, v[42:45] offset:512
	ds_write_b128 v38, v[46:49] offset:768
	ds_write_b128 v38, v[54:57] offset:1024
	v_pk_mul_f32 v[42:43], v[54:55], v[62:63]
	v_pk_mul_f32 v[44:45], v[56:57], v[64:65]
	ds_write_b128 v38, v[42:45] offset:1280
	s_waitcnt vmcnt(5)
	v_lshlrev_b32_e32 v42, 16, v18
	v_and_b32_e32 v43, 0xffff0000, v18
	v_lshlrev_b32_e32 v44, 16, v19
	v_and_b32_e32 v45, 0xffff0000, v19
	s_waitcnt vmcnt(1)
	v_lshlrev_b32_e32 v58, 16, v26
	v_and_b32_e32 v59, 0xffff0000, v26
	v_lshlrev_b32_e32 v60, 16, v27
	v_and_b32_e32 v61, 0xffff0000, v27
	s_waitcnt vmcnt(0)
	v_lshlrev_b32_e32 v62, 16, v28
	v_and_b32_e32 v63, 0xffff0000, v28
	v_lshlrev_b32_e32 v64, 16, v29
	v_and_b32_e32 v65, 0xffff0000, v29
	ds_write_b128 v38, v[42:45] offset:24576
	v_pk_add_f32 v[42:43], v[58:59], 1.0 op_sel_hi:[1,0] neg_lo:[1,0] neg_hi:[1,0]
	v_pk_add_f32 v[44:45], v[60:61], 1.0 op_sel_hi:[1,0] neg_lo:[1,0] neg_hi:[1,0]
	ds_write_b128 v38, v[42:45] offset:24832
	v_pk_add_f32 v[42:43], v[62:63], -1.0 op_sel_hi:[1,0]
	v_pk_add_f32 v[44:45], v[64:65], -1.0 op_sel_hi:[1,0]
	v_lshlrev_b32_e32 v50, 16, v20
	v_and_b32_e32 v51, 0xffff0000, v20
	v_lshlrev_b32_e32 v52, 16, v21
	v_and_b32_e32 v53, 0xffff0000, v21
	v_pk_fma_f32 v[42:43], v[0:1], v[42:43], 1.0 op_sel_hi:[1,1,0]
	v_pk_fma_f32 v[44:45], v[2:3], v[44:45], 1.0 op_sel_hi:[1,1,0]
	v_lshlrev_b32_e32 v54, 16, v24
	v_and_b32_e32 v55, 0xffff0000, v24
	v_lshlrev_b32_e32 v56, 16, v25
	v_and_b32_e32 v57, 0xffff0000, v25
	v_pk_mul_f32 v[42:43], v[42:43], v[50:51]
	v_pk_mul_f32 v[44:45], v[44:45], v[52:53]
	v_lshlrev_b32_e32 v46, 16, v22
	v_and_b32_e32 v47, 0xffff0000, v22
	v_lshlrev_b32_e32 v48, 16, v23
	v_and_b32_e32 v49, 0xffff0000, v23
	ds_write_b128 v38, v[42:45] offset:25088
	ds_write_b128 v38, v[46:49] offset:25344
	ds_write_b128 v38, v[54:57] offset:25600
	v_pk_mul_f32 v[42:43], v[54:55], v[62:63]
	v_pk_mul_f32 v[44:45], v[56:57], v[64:65]
	s_cmpk_eq_i32 s57, 0x40e0
	ds_write_b128 v38, v[42:45] offset:25856
	s_waitcnt lgkmcnt(0)
	s_barrier
	ds_read_b128 v[46:49], v34 offset:1024
	ds_read_b128 v[66:69], v34 offset:2560
	ds_read2st64_b32 v[86:87], v35 offset0:3 offset1:9
	ds_read_b128 v[54:57], v34 offset:512
	ds_read_b128 v[50:53], v34 offset:256
	ds_read_b128 v[58:61], v34 offset:1280
	ds_read_b128 v[62:65], v34
	ds_read_b128 v[74:77], v34 offset:2048
	ds_read_b128 v[70:73], v34 offset:1792
	ds_read_b128 v[78:81], v34 offset:2816
	ds_read_b128 v[82:85], v34 offset:1536
	s_cbranch_scc1 .LBB0_1306
	v_add_u32_e32 v20, s57, v179
	v_add_u32_e32 v21, 32, v20
	s_movk_i32 s38, 0xff
	v_cmp_lt_u32_e64 s[38:39], s38, v21
	v_add_u32_e32 v14, 48, v20
	s_nop 0
	v_cndmask_b32_e64 v4, v40, v41, s[38:39]
	v_cmp_lt_u32_e64 s[38:39], s3, v21
	v_add3_u32 v4, v4, v37, 16
	v_cndmask_b32_e32 v4, v4, v21, vcc
	v_add_u32_e32 v4, s2, v4
	v_lshl_or_b32 v42, v4, 10, v39
	v_cndmask_b32_e64 v15, v40, v41, s[38:39]
	v_add_u32_e32 v15, v15, v37
	v_cndmask_b32_e32 v14, v15, v14, vcc
	v_add_u32_e32 v14, s2, v14
	v_lshl_or_b32 v43, v14, 10, v39
	global_load_dwordx2 v[4:5], v42, s[48:49]
	global_load_dwordx2 v[6:7], v42, s[58:59]
	global_load_dwordx2 v[8:9], v42, s[62:63]
	global_load_dwordx2 v[10:11], v42, s[54:55]
	global_load_dwordx2 v[14:15], v42, s[60:61]
	global_load_dwordx2 v[16:17], v42, s[64:65]
	global_load_dwordx2 v[18:19], v43, s[48:49]
	global_load_dwordx2 v[20:21], v43, s[58:59]
	global_load_dwordx2 v[22:23], v43, s[62:63]
	global_load_dwordx2 v[24:25], v43, s[54:55]
	global_load_dwordx2 v[26:27], v43, s[60:61]
	global_load_dwordx2 v[28:29], v43, s[64:65]
	s_branch .LBB0_1306
